# mode-1 and mode-4 K-loop load segments also VALU-free (saddr LDS-DMA + precomputed B base); modes 0,1,3,4 done
# baseline (speedup 1.0000x reference)
; __device__ __forceinline__ int otid() { int t = threadIdx.x; asm volatile("" : "+v"(t)); return t; }
; #define PG8_STAGE(bufoff, gbase, voff) do { _Pragma("unroll") for (int _i = 0; _i < 2; ++_i) \
;         __builtin_amdgcn_global_load_lds((const unsigned*)((const char*)(gbase) + (voff)[_i]), (LAS unsigned*)(lds + (bufoff) + ldsw + _i * 8192), 16, 0, 0); } while (0)
; #define PG8_WAIT_V(n) asm volatile("s_waitcnt vmcnt(" #n ")" ::: "memory")
; #define PG8_BAR __builtin_amdgcn_s_barrier()
; template <int MODE, class EpiT, class Sched>
; __device__ __forceinline__ void gemm_phase(LAS unsigned char* lds, const Gemm g, const Sched& S, const EpiT& E) {
;     const int tid = otid(), wid = __builtin_amdgcn_readfirstlane(tid >> 6), lane = tid & 63, wr = wid >> 2, wc = wid & 3, fr = lane & 15, fq = lane >> 4;
;     const int K = g.K, nt = K / BK;
;     unsigned voffA[2], voffB[2];
; #pragma unroll
;     for (int i = 0; i < 2; ++i) { int R, C; stage_rc(tid * 16 + i * 8192, R, C); voffA[i] = (unsigned)(R * K + C) * 2u; voffB[i] = (unsigned)(R * K + C) * 2u; }
;     const size_t kstep = (size_t)(BK * 2);
;     const size_t hstep = (size_t)HALF * K * 2;
;     const size_t tstep = 2 * hstep;
;     const unsigned ldsw = (unsigned)wid * 1024u;
;     const int aoff = lds_byte(wr * 64 + fr, fq * 8), boff = lds_byte(wc * 32 + fr, fq * 8);
;     ...
;     PG8_STAGE(PG8_SB(0, 0), cB, voffB); PG8_STAGE(PG8_SA(0, 0), cA, voffA); PG8_STAGE(PG8_SB(0, 1), cB + hstep, voffB); PG8_STAGE(PG8_SA(0, 1), cA + hstep, voffA);
;     if (wr == 1) PG8_BAR;
;     PG8_WAIT_V(4); PG8_BAR;
;     PG8_STAGE(PG8_SB(1, 0), cB + kstep, voffB); PG8_STAGE(PG8_SA(1, 0), cA + kstep, voffA); PG8_STAGE(PG8_SB(1, 1), cB + hstep + kstep, voffB);
;     PG8_WAIT_V(6); PG8_BAR;
.LBB0_150:
	s_add_i32 m0, s69, 0x18000
	v_lshl_add_u64 v[2:3], v[2:3], 0, s[76:77]
	s_waitcnt vmcnt(4)
	s_barrier
	global_load_lds_dwordx4 v[2:3], off
	v_lshl_add_u64 v[2:3], v[4:5], 0, s[76:77]
	s_add_i32 m0, s69, 0x1a000
	s_add_i32 s57, s69, 0x8000
	global_load_lds_dwordx4 v[2:3], off
	v_lshl_add_u64 v[2:3], v[6:7], 0, s[76:77]
	s_mov_b32 m0, s57
	s_add_i32 s60, s69, 0xa000
	global_load_lds_dwordx4 v[2:3], off
	v_lshl_add_u64 v[2:3], v[8:9], 0, s[76:77]
	s_mov_b32 m0, s60
	s_lshl_b32 s88, s14, 2
	global_load_lds_dwordx4 v[2:3], off
	s_add_i32 m0, s69, 0x1c000
	v_lshl_add_u64 v[2:3], v[10:11], 0, s[76:77]
	global_load_lds_dwordx4 v[2:3], off
	v_lshl_add_u64 v[2:3], v[12:13], 0, s[76:77]
	s_add_i32 m0, s69, 0x1e000
	v_bfe_u32 v21, v14, 4, 2
	global_load_lds_dwordx4 v[2:3], off
	v_cvt_f32_u32_e32 v2, s88
	v_and_b32_e32 v181, 15, v14
	v_lshlrev_b32_e32 v23, 4, v21
	v_lshlrev_b32_e32 v24, 2, v14
	v_rcp_iflag_f32_e32 v2, v2
	s_and_b32 s20, s3, 3
	v_lshl_or_b32 v23, v181, 6, v23
	s_lshl_b32 s3, s23, 13
	v_mul_f32_e32 v2, 0x4f7ffffe, v2
	v_cvt_u32_f32_e32 v2, v2
	v_and_b32_e32 v24, 32, v24
	v_bitop3_b32 v25, v23, s3, v24 bitop3:0xde
	s_lshl_b32 s3, s20, 12
	s_lshl_b32 s56, s23, 6
	v_bitop3_b32 v220, v23, s3, v24 bitop3:0xde
	v_add_u32_e32 v251, 0x10000, v220
	s_lshl_b32 s3, s14, 3
	v_readfirstlane_b32 s23, v2
	v_add_u32_e32 v2, v17, v15
	v_writelane_b32 v246, s3, 39
	s_sub_i32 s3, 0, s88
	v_add_lshl_u32 v2, v2, v16, 1
	v_mov_b32_e32 v3, v1
	s_waitcnt vmcnt(6)
	s_mul_i32 s3, s3, s23
	v_lshl_add_u64 v[184:185], s[38:39], 0, v[2:3]
	v_add_u32_e32 v2, v20, v18
	s_lshr_b32 s21, s16, 6
	v_lshlrev_b32_e32 v22, 3, v21
	s_mul_hi_u32 s3, s23, s3
	v_add_lshl_u32 v2, v2, v19, 1
	v_lshl_or_b32 v221, s20, 5, v22
	s_add_i32 s61, s21, -2
	v_and_b32_e32 v222, 63, v14
	s_mov_b32 s50, 0
	v_cmp_eq_u32_e64 s[40:41], 0, v21
	s_ashr_i32 s51, s31, 31
	s_mov_b32 s73, s25
	s_add_i32 s3, s23, s3
	v_lshl_add_u64 v[186:187], s[38:39], 0, v[2:3]
	v_add_u32_e32 v223, 0, v25
	s_barrier
	v_writelane_b32 v246, s3, 41
	s_branch .LBB0_152

; #define PG8_STAGE(bufoff, gbase, voff) do { _Pragma("unroll") for (int _i = 0; _i < 2; ++_i) \
;         __builtin_amdgcn_global_load_lds((const unsigned*)((const char*)(gbase) + (voff)[_i]), (LAS unsigned*)(lds + (bufoff) + ldsw + _i * 8192), 16, 0, 0); } while (0)
; #define PG8_LDA(dst, b, h) do { _Pragma("unroll") for (int m = 0; m < 4; ++m) _Pragma("unroll") for (int k = 0; k < 2; ++k) dst[m][k] = *(const LAS bf16x8*)(lds + PG8_SA(b, h) + aoff + m * 2048 + k * 1024); } while (0)
; #define PG8_LDB(dst, b, h) do { _Pragma("unroll") for (int n = 0; n < 2; ++n) _Pragma("unroll") for (int k = 0; k < 2; ++k) dst[n][k] = *(const LAS bf16x8*)(lds + PG8_SB(b, h) + boff + n * 2048 + k * 1024); } while (0)
; #define PG8_MMA(ai, bj, At, Bt) do { __builtin_amdgcn_s_setprio(1); _Pragma("unroll") for (int m = 0; m < 4; ++m) _Pragma("unroll") for (int n = 0; n < 2; ++n) _Pragma("unroll") for (int k = 0; k < 2; ++k) \
;         acc[ai][bj][m][n] = __builtin_amdgcn_mfma_f32_16x16x32_bf16(Bt[n][k], At[m][k], acc[ai][bj][m][n], 0, 0, 0); __builtin_amdgcn_s_setprio(0); } while (0)
; #define PG8_WAIT_V(n) asm volatile("s_waitcnt vmcnt(" #n ")" ::: "memory")
; #define PG8_WAIT_L(n) asm volatile("s_waitcnt lgkmcnt(" #n ")" ::: "memory")
; template <int MODE, class EpiT, class Sched>
; __device__ __forceinline__ void gemm_phase(LAS unsigned char* lds, const Gemm g, const Sched& S, const EpiT& E) {
;     ...
;         for (int t = 0; t < nt; t += 2) {
;             const bool last = (t == nt - 2);
;             const char* a1 = cA + (size_t)(t + 1) * kstep;
;             const char* a2 = last ? nA : cA + (size_t)(t + 2) * kstep; const char* b2 = last ? nB : cB + (size_t)(t + 2) * kstep;
;             const char* a3 = a2 + kstep; const char* b3 = b2 + kstep;
;             PG8_LDB(B0, 0, 0); PG8_SCHED; PG8_LDA(At, 0, 0); PG8_STAGE(PG8_SA(1, 1), a1 + hstep, voffA);
;             PG8_WAIT_L(8); PG8_BAR; PG8_WAIT_L(0); PG8_MMA(0, 0, At, B0); PG8_BAR; PG8_SCHED;
;             PG8_LDB(B1, 0, 1); PG8_STAGE(PG8_SB(0, 0), b2, voffB);
;             PG8_BAR; PG8_WAIT_L(0); PG8_MMA(0, 1, At, B1); PG8_BAR;
;             PG8_LDA(At, 0, 1); PG8_STAGE(PG8_SA(0, 0), a2, voffA);
;             PG8_BAR; PG8_WAIT_L(0); PG8_MMA(1, 0, At, B0); PG8_BAR; PG8_SCHED;
;             PG8_STAGE(PG8_SB(0, 1), b2 + hstep, voffB);
;             PG8_WAIT_V(6); PG8_BAR; PG8_MMA(1, 1, At, B1); PG8_BAR;
.LBB0_159:
	s_add_i32 s89, s30, 2
	s_add_u32 s44, s4, 0x80
	s_addc_u32 s45, s5, 0
	s_add_u32 s100, s4, s38
	s_addc_u32 s101, s5, 0
	s_add_i32 s58, 0, 0x10000
	ds_read_b128 v[130:133], v251
	ds_read_b128 v[134:137], v251 offset:1024
	ds_read_b128 v[138:141], v251 offset:2048
	ds_read_b128 v[142:145], v251 offset:3072
	s_cmp_eq_u32 s61, s30
	s_cselect_b32 s45, s79, s45
	s_cselect_b32 s44, s78, s44
	s_cselect_b32 s53, s47, s24
	s_cselect_b32 s52, s46, s23
	s_add_i32 m0, s69, 0xc000
	ds_read_b128 v[146:149], v223
	ds_read_b128 v[150:153], v223 offset:1024
	ds_read_b128 v[154:157], v223 offset:2048
	ds_read_b128 v[158:161], v223 offset:3072
	ds_read_b128 v[162:165], v223 offset:4096
	ds_read_b128 v[166:169], v223 offset:5120
	ds_read_b128 v[170:173], v223 offset:6144
	ds_read_b128 v[174:177], v223 offset:7168
	global_load_lds_dwordx4 v0, s[100:101]
	s_add_i32 m0, s69, 0xe000
	s_nop 0
	global_load_lds_dwordx4 v182, s[100:101]
	s_waitcnt lgkmcnt(8)
	s_barrier
	s_waitcnt lgkmcnt(0)
	v_mfma_f32_16x16x32_bf16 v[126:129], v[130:133], v[146:149], v[126:129]
	v_mfma_f32_16x16x32_bf16 v[122:125], v[138:141], v[146:149], v[122:125]
	v_mfma_f32_16x16x32_bf16 v[110:113], v[130:133], v[154:157], v[110:113]
	v_mfma_f32_16x16x32_bf16 v[106:109], v[138:141], v[154:157], v[106:109]
	v_mfma_f32_16x16x32_bf16 v[94:97], v[130:133], v[162:165], v[94:97]
	v_mfma_f32_16x16x32_bf16 v[90:93], v[138:141], v[162:165], v[90:93]
	v_mfma_f32_16x16x32_bf16 v[78:81], v[130:133], v[170:173], v[78:81]
	v_mfma_f32_16x16x32_bf16 v[74:77], v[138:141], v[170:173], v[74:77]
	v_mfma_f32_16x16x32_bf16 v[126:129], v[134:137], v[150:153], v[126:129]
	v_mfma_f32_16x16x32_bf16 v[122:125], v[142:145], v[150:153], v[122:125]
	v_mfma_f32_16x16x32_bf16 v[110:113], v[134:137], v[158:161], v[110:113]
	v_mfma_f32_16x16x32_bf16 v[106:109], v[142:145], v[158:161], v[106:109]
	v_mfma_f32_16x16x32_bf16 v[94:97], v[134:137], v[166:169], v[94:97]
	v_mfma_f32_16x16x32_bf16 v[90:93], v[142:145], v[166:169], v[90:93]
	v_mfma_f32_16x16x32_bf16 v[78:81], v[134:137], v[174:177], v[78:81]
	v_mfma_f32_16x16x32_bf16 v[74:77], v[142:145], v[174:177], v[74:77]
	s_barrier
	s_add_i32 s30, 0, 0x14000
	s_add_i32 s58, s58, s68
	s_add_u32 s98, s52, 0x80
	s_addc_u32 s99, s53, 0
	s_mov_b32 m0, s58
	ds_read_b128 v[188:191], v251 offset:16384
	ds_read_b128 v[192:195], v251 offset:17408
	ds_read_b128 v[196:199], v251 offset:18432
	ds_read_b128 v[224:227], v251 offset:19456
	global_load_lds_dwordx4 v0, s[52:53]
	s_add_i32 m0, s58, 0x2000
	s_nop 0
	global_load_lds_dwordx4 v182, s[52:53]
	s_barrier
	s_waitcnt lgkmcnt(0)
	v_mfma_f32_16x16x32_bf16 v[118:121], v[188:191], v[146:149], v[118:121]
	v_mfma_f32_16x16x32_bf16 v[114:117], v[196:199], v[146:149], v[114:117]
	v_mfma_f32_16x16x32_bf16 v[102:105], v[188:191], v[154:157], v[102:105]
	v_mfma_f32_16x16x32_bf16 v[98:101], v[196:199], v[154:157], v[98:101]
	v_mfma_f32_16x16x32_bf16 v[86:89], v[188:191], v[162:165], v[86:89]
	v_mfma_f32_16x16x32_bf16 v[82:85], v[196:199], v[162:165], v[82:85]
	v_mfma_f32_16x16x32_bf16 v[70:73], v[188:191], v[170:173], v[70:73]
	v_mfma_f32_16x16x32_bf16 v[66:69], v[196:199], v[170:173], v[66:69]
	v_mfma_f32_16x16x32_bf16 v[118:121], v[192:195], v[150:153], v[118:121]
	v_mfma_f32_16x16x32_bf16 v[114:117], v[224:227], v[150:153], v[114:117]
	v_mfma_f32_16x16x32_bf16 v[102:105], v[192:195], v[158:161], v[102:105]
	v_mfma_f32_16x16x32_bf16 v[98:101], v[224:227], v[158:161], v[98:101]
	v_mfma_f32_16x16x32_bf16 v[86:89], v[192:195], v[166:169], v[86:89]
	v_mfma_f32_16x16x32_bf16 v[82:85], v[224:227], v[166:169], v[82:85]
	v_mfma_f32_16x16x32_bf16 v[70:73], v[192:195], v[174:177], v[70:73]
	v_mfma_f32_16x16x32_bf16 v[66:69], v[224:227], v[174:177], v[66:69]
	s_barrier
	s_mov_b32 m0, s69
	s_add_u32 s100, s44, 0x80
	s_addc_u32 s101, s45, 0
	ds_read_b128 v[146:149], v223 offset:16384
	ds_read_b128 v[150:153], v223 offset:17408
	ds_read_b128 v[154:157], v223 offset:18432
	ds_read_b128 v[158:161], v223 offset:19456
	ds_read_b128 v[162:165], v223 offset:20480
	ds_read_b128 v[166:169], v223 offset:21504
	ds_read_b128 v[170:173], v223 offset:22528
	ds_read_b128 v[174:177], v223 offset:23552
	global_load_lds_dwordx4 v0, s[44:45]
	s_mov_b32 m0, s74
	s_nop 0
	global_load_lds_dwordx4 v182, s[44:45]
	s_barrier
	s_waitcnt lgkmcnt(0)
	v_mfma_f32_16x16x32_bf16 v[62:65], v[130:133], v[146:149], v[62:65]
	v_mfma_f32_16x16x32_bf16 v[58:61], v[138:141], v[146:149], v[58:61]
	v_mfma_f32_16x16x32_bf16 v[46:49], v[130:133], v[154:157], v[46:49]
	v_mfma_f32_16x16x32_bf16 v[42:45], v[138:141], v[154:157], v[42:45]
	v_mfma_f32_16x16x32_bf16 v[30:33], v[130:133], v[162:165], v[30:33]
	v_mfma_f32_16x16x32_bf16 v[26:29], v[138:141], v[162:165], v[26:29]
	v_mfma_f32_16x16x32_bf16 v[14:17], v[130:133], v[170:173], v[14:17]
	v_mfma_f32_16x16x32_bf16 v[10:13], v[138:141], v[170:173], v[10:13]
	v_mfma_f32_16x16x32_bf16 v[62:65], v[134:137], v[150:153], v[62:65]
	v_mfma_f32_16x16x32_bf16 v[58:61], v[142:145], v[150:153], v[58:61]
	v_mfma_f32_16x16x32_bf16 v[46:49], v[134:137], v[158:161], v[46:49]
	v_mfma_f32_16x16x32_bf16 v[42:45], v[142:145], v[158:161], v[42:45]
	v_mfma_f32_16x16x32_bf16 v[30:33], v[134:137], v[166:169], v[30:33]
	v_mfma_f32_16x16x32_bf16 v[26:29], v[142:145], v[166:169], v[26:29]
	v_mfma_f32_16x16x32_bf16 v[14:17], v[134:137], v[174:177], v[14:17]
	v_mfma_f32_16x16x32_bf16 v[10:13], v[142:145], v[174:177], v[10:13]
	s_barrier
	s_add_u32 s52, s52, s38
	s_addc_u32 s53, s53, 0
	s_add_i32 s30, s30, s68
	s_mov_b32 m0, s30
	s_nop 0
	global_load_lds_dwordx4 v0, s[52:53]
	s_add_i32 m0, s30, 0x2000
	s_nop 0
	global_load_lds_dwordx4 v182, s[52:53]
	s_waitcnt vmcnt(6)
	s_barrier
; #define PG8_STAGE(bufoff, gbase, voff) do { _Pragma("unroll") for (int _i = 0; _i < 2; ++_i) \
;         __builtin_amdgcn_global_load_lds((const unsigned*)((const char*)(gbase) + (voff)[_i]), (LAS unsigned*)(lds + (bufoff) + ldsw + _i * 8192), 16, 0, 0); } while (0)
; #define PG8_LDA(dst, b, h) do { _Pragma("unroll") for (int m = 0; m < 4; ++m) _Pragma("unroll") for (int k = 0; k < 2; ++k) dst[m][k] = *(const LAS bf16x8*)(lds + PG8_SA(b, h) + aoff + m * 2048 + k * 1024); } while (0)
; #define PG8_LDB(dst, b, h) do { _Pragma("unroll") for (int n = 0; n < 2; ++n) _Pragma("unroll") for (int k = 0; k < 2; ++k) dst[n][k] = *(const LAS bf16x8*)(lds + PG8_SB(b, h) + boff + n * 2048 + k * 1024); } while (0)
; #define PG8_MMA(ai, bj, At, Bt) do { __builtin_amdgcn_s_setprio(1); _Pragma("unroll") for (int m = 0; m < 4; ++m) _Pragma("unroll") for (int n = 0; n < 2; ++n) _Pragma("unroll") for (int k = 0; k < 2; ++k) \
;         acc[ai][bj][m][n] = __builtin_amdgcn_mfma_f32_16x16x32_bf16(Bt[n][k], At[m][k], acc[ai][bj][m][n], 0, 0, 0); __builtin_amdgcn_s_setprio(0); } while (0)
; #define PG8_WAIT_V(n) asm volatile("s_waitcnt vmcnt(" #n ")" ::: "memory")
; #define PG8_WAIT_L(n) asm volatile("s_waitcnt lgkmcnt(" #n ")" ::: "memory")
; #define PG8_BAR __builtin_amdgcn_s_barrier()
; #define PG8_SCHED __builtin_amdgcn_sched_barrier(0)
; template <int MODE, class EpiT, class Sched>
; __device__ __forceinline__ void gemm_phase(LAS unsigned char* lds, const Gemm g, const Sched& S, const EpiT& E) {
;     ...
;             PG8_WAIT_V(6); PG8_BAR; PG8_MMA(1, 1, At, B1); PG8_BAR;
;             PG8_LDB(B0, 1, 0); PG8_SCHED; PG8_LDA(At, 1, 0); PG8_STAGE(PG8_SA(0, 1), a2 + hstep, voffA);
;             PG8_WAIT_L(8); PG8_BAR; PG8_WAIT_L(0); PG8_MMA(0, 0, At, B0); PG8_BAR; PG8_SCHED;
;             PG8_LDB(B1, 1, 1); PG8_STAGE(PG8_SB(1, 0), b3, voffB);
;             PG8_BAR; PG8_WAIT_L(0); PG8_MMA(0, 1, At, B1); PG8_BAR;
;             PG8_LDA(At, 1, 1); PG8_STAGE(PG8_SA(1, 0), a3, voffA);
;             PG8_BAR; PG8_WAIT_L(0); PG8_MMA(1, 0, At, B0); PG8_BAR; PG8_SCHED;
	v_mfma_f32_16x16x32_bf16 v[54:57], v[188:191], v[146:149], v[54:57]
	v_mfma_f32_16x16x32_bf16 v[50:53], v[196:199], v[146:149], v[50:53]
	v_mfma_f32_16x16x32_bf16 v[38:41], v[188:191], v[154:157], v[38:41]
	v_mfma_f32_16x16x32_bf16 v[34:37], v[196:199], v[154:157], v[34:37]
	v_mfma_f32_16x16x32_bf16 v[22:25], v[188:191], v[162:165], v[22:25]
	v_mfma_f32_16x16x32_bf16 v[18:21], v[196:199], v[162:165], v[18:21]
	v_mfma_f32_16x16x32_bf16 v[6:9], v[188:191], v[170:173], v[6:9]
	v_mfma_f32_16x16x32_bf16 v[2:5], v[196:199], v[170:173], v[2:5]
	v_mfma_f32_16x16x32_bf16 v[54:57], v[192:195], v[150:153], v[54:57]
	v_mfma_f32_16x16x32_bf16 v[50:53], v[224:227], v[150:153], v[50:53]
	v_mfma_f32_16x16x32_bf16 v[38:41], v[192:195], v[158:161], v[38:41]
	v_mfma_f32_16x16x32_bf16 v[34:37], v[224:227], v[158:161], v[34:37]
	v_mfma_f32_16x16x32_bf16 v[22:25], v[192:195], v[166:169], v[22:25]
	v_mfma_f32_16x16x32_bf16 v[18:21], v[224:227], v[166:169], v[18:21]
	v_mfma_f32_16x16x32_bf16 v[6:9], v[192:195], v[174:177], v[6:9]
	v_mfma_f32_16x16x32_bf16 v[2:5], v[224:227], v[174:177], v[2:5]
	s_barrier
	s_add_i32 s30, 0, 0x18000
	ds_read_b128 v[130:133], v251 offset:32768
	ds_read_b128 v[134:137], v251 offset:33792
	ds_read_b128 v[138:141], v251 offset:34816
	ds_read_b128 v[142:145], v251 offset:35840
	s_add_u32 s44, s44, s38
	s_addc_u32 s45, s45, 0
	s_mov_b32 m0, s75
	ds_read_b128 v[146:149], v223 offset:32768
	ds_read_b128 v[150:153], v223 offset:33792
	ds_read_b128 v[154:157], v223 offset:34816
	ds_read_b128 v[158:161], v223 offset:35840
	ds_read_b128 v[162:165], v223 offset:36864
	ds_read_b128 v[166:169], v223 offset:37888
	ds_read_b128 v[170:173], v223 offset:38912
	ds_read_b128 v[174:177], v223 offset:39936
	global_load_lds_dwordx4 v0, s[44:45]
	s_mov_b32 m0, s9
	s_nop 0
	global_load_lds_dwordx4 v182, s[44:45]
	s_waitcnt lgkmcnt(8)
	s_barrier
	s_waitcnt lgkmcnt(0)
	v_mfma_f32_16x16x32_bf16 v[126:129], v[130:133], v[146:149], v[126:129]
	v_mfma_f32_16x16x32_bf16 v[122:125], v[138:141], v[146:149], v[122:125]
	v_mfma_f32_16x16x32_bf16 v[110:113], v[130:133], v[154:157], v[110:113]
	v_mfma_f32_16x16x32_bf16 v[106:109], v[138:141], v[154:157], v[106:109]
	v_mfma_f32_16x16x32_bf16 v[94:97], v[130:133], v[162:165], v[94:97]
	v_mfma_f32_16x16x32_bf16 v[90:93], v[138:141], v[162:165], v[90:93]
	v_mfma_f32_16x16x32_bf16 v[78:81], v[130:133], v[170:173], v[78:81]
	v_mfma_f32_16x16x32_bf16 v[74:77], v[138:141], v[170:173], v[74:77]
	v_mfma_f32_16x16x32_bf16 v[126:129], v[134:137], v[150:153], v[126:129]
	v_mfma_f32_16x16x32_bf16 v[122:125], v[142:145], v[150:153], v[122:125]
	v_mfma_f32_16x16x32_bf16 v[110:113], v[134:137], v[158:161], v[110:113]
	v_mfma_f32_16x16x32_bf16 v[106:109], v[142:145], v[158:161], v[106:109]
	v_mfma_f32_16x16x32_bf16 v[94:97], v[134:137], v[166:169], v[94:97]
	v_mfma_f32_16x16x32_bf16 v[90:93], v[142:145], v[166:169], v[90:93]
	v_mfma_f32_16x16x32_bf16 v[78:81], v[134:137], v[174:177], v[78:81]
	v_mfma_f32_16x16x32_bf16 v[74:77], v[142:145], v[174:177], v[74:77]
	s_barrier
	s_add_i32 s44, 0, 0x1c000
	s_add_i32 s30, s30, s68
	s_mov_b32 m0, s30
	ds_read_b128 v[188:191], v251 offset:49152
	ds_read_b128 v[192:195], v251 offset:50176
	ds_read_b128 v[196:199], v251 offset:51200
	ds_read_b128 v[224:227], v251 offset:52224
	global_load_lds_dwordx4 v0, s[98:99]
	s_add_i32 m0, s30, 0x2000
	s_nop 0
	global_load_lds_dwordx4 v182, s[98:99]
	s_barrier
	s_waitcnt lgkmcnt(0)
	v_mfma_f32_16x16x32_bf16 v[118:121], v[188:191], v[146:149], v[118:121]
	v_mfma_f32_16x16x32_bf16 v[114:117], v[196:199], v[146:149], v[114:117]
	v_mfma_f32_16x16x32_bf16 v[102:105], v[188:191], v[154:157], v[102:105]
	v_mfma_f32_16x16x32_bf16 v[98:101], v[196:199], v[154:157], v[98:101]
	v_mfma_f32_16x16x32_bf16 v[86:89], v[188:191], v[162:165], v[86:89]
	v_mfma_f32_16x16x32_bf16 v[82:85], v[196:199], v[162:165], v[82:85]
	v_mfma_f32_16x16x32_bf16 v[70:73], v[188:191], v[170:173], v[70:73]
	v_mfma_f32_16x16x32_bf16 v[66:69], v[196:199], v[170:173], v[66:69]
	v_mfma_f32_16x16x32_bf16 v[118:121], v[192:195], v[150:153], v[118:121]
	v_mfma_f32_16x16x32_bf16 v[114:117], v[224:227], v[150:153], v[114:117]
	v_mfma_f32_16x16x32_bf16 v[102:105], v[192:195], v[158:161], v[102:105]
	v_mfma_f32_16x16x32_bf16 v[98:101], v[224:227], v[158:161], v[98:101]
	v_mfma_f32_16x16x32_bf16 v[86:89], v[192:195], v[166:169], v[86:89]
	v_mfma_f32_16x16x32_bf16 v[82:85], v[224:227], v[166:169], v[82:85]
	v_mfma_f32_16x16x32_bf16 v[70:73], v[192:195], v[174:177], v[70:73]
	v_mfma_f32_16x16x32_bf16 v[66:69], v[224:227], v[174:177], v[66:69]
	s_barrier
	s_mov_b32 m0, s57
	ds_read_b128 v[146:149], v223 offset:49152
	ds_read_b128 v[150:153], v223 offset:50176
	ds_read_b128 v[154:157], v223 offset:51200
	ds_read_b128 v[158:161], v223 offset:52224
	ds_read_b128 v[162:165], v223 offset:53248
	ds_read_b128 v[166:169], v223 offset:54272
	ds_read_b128 v[170:173], v223 offset:55296
	ds_read_b128 v[174:177], v223 offset:56320
	global_load_lds_dwordx4 v0, s[100:101]
	s_mov_b32 m0, s60
	s_nop 0
	global_load_lds_dwordx4 v182, s[100:101]
	s_barrier
	s_waitcnt lgkmcnt(0)
	v_mfma_f32_16x16x32_bf16 v[62:65], v[130:133], v[146:149], v[62:65]
	v_mfma_f32_16x16x32_bf16 v[58:61], v[138:141], v[146:149], v[58:61]
	v_mfma_f32_16x16x32_bf16 v[46:49], v[130:133], v[154:157], v[46:49]
	v_mfma_f32_16x16x32_bf16 v[42:45], v[138:141], v[154:157], v[42:45]
	v_mfma_f32_16x16x32_bf16 v[30:33], v[130:133], v[162:165], v[30:33]
	v_mfma_f32_16x16x32_bf16 v[26:29], v[138:141], v[162:165], v[26:29]
	v_mfma_f32_16x16x32_bf16 v[14:17], v[130:133], v[170:173], v[14:17]
	v_mfma_f32_16x16x32_bf16 v[10:13], v[138:141], v[170:173], v[10:13]
	v_mfma_f32_16x16x32_bf16 v[62:65], v[134:137], v[150:153], v[62:65]
	v_mfma_f32_16x16x32_bf16 v[58:61], v[142:145], v[150:153], v[58:61]
	v_mfma_f32_16x16x32_bf16 v[46:49], v[134:137], v[158:161], v[46:49]
	v_mfma_f32_16x16x32_bf16 v[42:45], v[142:145], v[158:161], v[42:45]
	v_mfma_f32_16x16x32_bf16 v[30:33], v[134:137], v[166:169], v[30:33]
	v_mfma_f32_16x16x32_bf16 v[26:29], v[142:145], v[166:169], v[26:29]
	v_mfma_f32_16x16x32_bf16 v[14:17], v[134:137], v[174:177], v[14:17]
	v_mfma_f32_16x16x32_bf16 v[10:13], v[142:145], v[174:177], v[10:13]
	s_barrier
;     __device__ __forceinline__ void scales2(const Unit& u, int wr, int fr, int fq, float& sA, float& sB) const {
;         const int rowA = u.pm * BM + wr * 64 + fq * 16 + fr;
;         const f32x4* pa = (const f32x4*)(ssq_in + (size_t)rowA * 16); const f32x4* pb = (const f32x4*)(ssq_in + (size_t)(rowA + HALF) * 16);
;         const f32x4 a0 = pa[0], a1 = pa[1], a2 = pa[2], a3 = pa[3], b0 = pb[0], b1 = pb[1], b2 = pb[2], b3 = pb[3];
;         const float ta = (((a0[0] + a0[1]) + (a0[2] + a0[3])) + ((a1[0] + a1[1]) + (a1[2] + a1[3]))) + (((a2[0] + a2[1]) + (a2[2] + a2[3])) + ((a3[0] + a3[1]) + (a3[2] + a3[3])));
;         const float tb = (((b0[0] + b0[1]) + (b0[2] + b0[3])) + ((b1[0] + b1[1]) + (b1[2] + b1[3]))) + (((b2[0] + b2[1]) + (b2[2] + b2[3])) + ((b3[0] + b3[1]) + (b3[2] + b3[3])));
;         sA = rsqrtf(ta * (1.0f / 1024.0f) + EPS); sB = rsqrtf(tb * (1.0f / 1024.0f) + EPS);
;     template <int mode> __device__ __forceinline__ void run(const f32x4 (&acc)[2][2][4][2], const Unit& u, int wr, int wc, int fr, int fq, const LAS float* sc) const {
;     ...
;             {
;                 const size_t off = (size_t)row0 * D + col0;
; #pragma unroll
;                 for (int bj = 0; bj < 2; ++bj) {
;                     const size_t o = off + bj * HALF;
;                     if (mode == 5) { xi[0][2 * bj] = *(const f32x4*)(xin + o); xi[0][2 * bj + 1] = *(const f32x4*)(xin + o + 4); }
;                     else { xh[0][bj] = *(const u32x4*)(hin + o); xl[0][bj] = *(const u32x4*)(lin + o); }
;                     if (mode == 4) pq[0][bj] = *(const u32x4*)(ob + o);
;                 }
;             }
; #pragma unroll
;             for (int g = 0; g < 8; ++g) {
;                 const int ai = g >> 2, m = g & 3, cb = g & 1, nb = cb ^ 1;
;                 const int row = row0 + ai * HALF + m * 16;
;                 const size_t off = (size_t)row * D + col0;
;                 if (g < 7) {
;                     const size_t offn = (size_t)(row0 + ((g + 1) >> 2) * HALF + ((g + 1) & 3) * 16) * D + col0;
; #pragma unroll
;                     for (int bj = 0; bj < 2; ++bj) {
;                         const size_t o = offn + bj * HALF;
;                         if (mode == 5) { xi[nb][2 * bj] = *(const f32x4*)(xin + o); xi[nb][2 * bj + 1] = *(const f32x4*)(xin + o + 4); }
	s_add_i32 s30, s44, s68
	s_add_u32 s98, s98, s38
	s_addc_u32 s99, s99, 0
	s_mov_b32 m0, s30
	s_nop 0
	global_load_lds_dwordx4 v0, s[98:99]
	s_add_i32 m0, s30, 0x2000
	s_nop 0
	global_load_lds_dwordx4 v182, s[98:99]
	s_waitcnt vmcnt(6)
	s_barrier
	v_mfma_f32_16x16x32_bf16 v[54:57], v[188:191], v[146:149], v[54:57]
	v_mfma_f32_16x16x32_bf16 v[50:53], v[196:199], v[146:149], v[50:53]
	v_mfma_f32_16x16x32_bf16 v[38:41], v[188:191], v[154:157], v[38:41]
	v_mfma_f32_16x16x32_bf16 v[34:37], v[196:199], v[154:157], v[34:37]
	v_mfma_f32_16x16x32_bf16 v[22:25], v[188:191], v[162:165], v[22:25]
	v_mfma_f32_16x16x32_bf16 v[18:21], v[196:199], v[162:165], v[18:21]
	v_mfma_f32_16x16x32_bf16 v[6:9], v[188:191], v[170:173], v[6:9]
	v_mfma_f32_16x16x32_bf16 v[2:5], v[196:199], v[170:173], v[2:5]
	v_mfma_f32_16x16x32_bf16 v[54:57], v[192:195], v[150:153], v[54:57]
	v_mfma_f32_16x16x32_bf16 v[50:53], v[224:227], v[150:153], v[50:53]
	v_mfma_f32_16x16x32_bf16 v[38:41], v[192:195], v[158:161], v[38:41]
	v_mfma_f32_16x16x32_bf16 v[34:37], v[224:227], v[158:161], v[34:37]
	v_mfma_f32_16x16x32_bf16 v[22:25], v[192:195], v[166:169], v[22:25]
	v_mfma_f32_16x16x32_bf16 v[18:21], v[224:227], v[166:169], v[18:21]
	v_mfma_f32_16x16x32_bf16 v[6:9], v[192:195], v[174:177], v[6:9]
	v_mfma_f32_16x16x32_bf16 v[2:5], v[224:227], v[174:177], v[2:5]
	s_barrier
	s_add_u32 s4, s4, 0x100
	s_addc_u32 s5, s5, 0
	s_add_u32 s23, s23, 0x100
	s_addc_u32 s24, s24, 0
	s_cmp_ge_u32 s89, s21
	s_mov_b32 s30, s89
	s_cbranch_scc0 .LBB0_159
	s_lshl_b32 s4, s22, 8
	s_add_i32 s4, s4, s56
	v_or_b32_e32 v130, s4, v222
	v_ashrrev_i32_e32 v131, 31, v130
	v_lshlrev_b64 v[130:131], 6, v[130:131]
	v_lshl_add_u64 v[146:147], s[66:67], 0, v[130:131]
	global_load_dwordx4 v[130:133], v[146:147], off offset:16
	global_load_dwordx4 v[134:137], v[146:147], off offset:48
	global_load_dwordx4 v[138:141], v[146:147], off
	global_load_dwordx4 v[142:145], v[146:147], off offset:32
	v_or_b32_e32 v192, s4, v181
	s_mov_b64 s[4:5], 0x2000
	v_lshl_add_u64 v[158:159], v[146:147], 0, s[4:5]
	v_add_co_u32_e32 v146, vcc, 0x2000, v146
	s_mov_b32 s4, 0x3a800000
	s_nop 0
	v_addc_co_u32_e32 v147, vcc, 0, v147, vcc
	global_load_dwordx4 v[146:149], v[146:147], off
	s_nop 0
	global_load_dwordx4 v[150:153], v[158:159], off offset:16
	global_load_dwordx4 v[154:157], v[158:159], off offset:48
	s_nop 0
	global_load_dwordx4 v[158:161], v[158:159], off offset:32
	v_lshl_or_b32 v188, s2, 8, v221
	v_ashrrev_i32_e32 v193, 31, v192
	v_ashrrev_i32_e32 v189, 31, v188
	v_or_b32_e32 v194, 16, v192
	v_ashrrev_i32_e32 v195, 31, v194
	s_waitcnt vmcnt(0)
	v_mov_b32_e32 v162, v138
	v_mov_b32_e32 v163, v142
	v_mov_b32_e32 v142, v139
	v_pk_add_f32 v[138:139], v[162:163], v[142:143]
	v_mov_b32_e32 v142, v140
	v_mov_b32_e32 v143, v144
	v_mov_b32_e32 v144, v141
	v_pk_add_f32 v[140:141], v[142:143], v[144:145]
	s_nop 0
	v_pk_add_f32 v[138:139], v[138:139], v[140:141]
	v_mov_b32_e32 v140, v130
	v_mov_b32_e32 v141, v134
	v_mov_b32_e32 v134, v131
	v_pk_add_f32 v[130:131], v[140:141], v[134:135]
	v_mov_b32_e32 v134, v132
	v_mov_b32_e32 v135, v136
	v_mov_b32_e32 v136, v133
	v_pk_add_f32 v[132:133], v[134:135], v[136:137]
	v_mov_b32_e32 v134, v148
	v_pk_add_f32 v[130:131], v[130:131], v[132:133]
	v_mov_b32_e32 v132, v146
	v_mov_b32_e32 v133, v158
	v_mov_b32_e32 v158, v147
	v_mov_b32_e32 v135, v160
	v_mov_b32_e32 v160, v149
	v_pk_add_f32 v[132:133], v[132:133], v[158:159]
	v_pk_add_f32 v[134:135], v[134:135], v[160:161]
	v_mov_b32_e32 v136, v152
	v_pk_add_f32 v[132:133], v[132:133], v[134:135]
	v_mov_b32_e32 v134, v150
	v_mov_b32_e32 v135, v154
	v_mov_b32_e32 v154, v151
	v_mov_b32_e32 v137, v156
	v_mov_b32_e32 v156, v153
	v_pk_add_f32 v[134:135], v[134:135], v[154:155]
	v_pk_add_f32 v[136:137], v[136:137], v[156:157]
	v_pk_add_f32 v[130:131], v[138:139], v[130:131]
	v_pk_add_f32 v[134:135], v[134:135], v[136:137]
	s_nop 0
	v_pk_add_f32 v[132:133], v[132:133], v[134:135]
	v_mov_b32_e32 v135, v130
	v_mov_b32_e32 v134, v132
	v_mov_b32_e32 v130, v133
	v_pk_add_f32 v[130:131], v[134:135], v[130:131]
	s_nop 0
	v_pk_fma_f32 v[190:191], v[130:131], s[4:5], v[178:179] op_sel_hi:[1,0,0]
	s_mov_b32 s4, 0x800000
	v_mul_f32_e32 v130, 0x4b800000, v191
	v_cmp_gt_f32_e64 s[44:45], s4, v191
	v_cmp_gt_f32_e32 vcc, s4, v190
	s_nop 0
	v_cndmask_b32_e64 v130, v191, v130, s[44:45]
	v_rsq_f32_e32 v130, v130
	s_nop 0
	v_mul_f32_e32 v131, 0x45800000, v130
	v_cndmask_b32_e64 v226, v130, v131, s[44:45]
	v_lshlrev_b64 v[130:131], 10, v[192:193]
	v_lshl_add_u64 v[130:131], v[130:131], 0, v[188:189]
	v_lshlrev_b64 v[198:199], 1, v[130:131]
	v_lshl_add_u64 v[130:131], s[34:35], 0, v[198:199]
	v_lshl_add_u64 v[132:133], s[92:93], 0, v[198:199]
	global_load_dwordx4 v[170:173], v[130:131], off
	global_load_dwordx4 v[174:177], v[132:133], off
	v_lshl_add_u64 v[134:135], s[6:7], 0, v[198:199]
	global_load_dwordx4 v[166:169], v[134:135], off
	global_load_dwordx4 v[158:161], v[130:131], off offset:256
	global_load_dwordx4 v[162:165], v[132:133], off offset:256
	global_load_dwordx4 v[146:149], v[134:135], off offset:256
	v_and_b32_e32 v130, 64, v205
	v_or_b32_e32 v200, v130, v181
	v_lshlrev_b32_e32 v225, 2, v200
	ds_bpermute_b32 v200, v225, v226
	v_xor_b32_e32 v131, 16, v205
	v_add_u32_e32 v130, 64, v130
	v_cmp_lt_i32_e64 s[44:45], v131, v130
	s_waitcnt lgkmcnt(0)
;     template <int mode> __device__ __forceinline__ void run(const f32x4 (&acc)[2][2][4][2], const Unit& u, int wr, int wc, int fr, int fq, const LAS float* sc) const {
;     ...
; #pragma unroll
;             for (int g = 0; g < 8; ++g) {
;                 const int ai = g >> 2, m = g & 3, cb = g & 1, nb = cb ^ 1;
;                 const int row = row0 + ai * HALF + m * 16;
;                 const size_t off = (size_t)row * D + col0;
;                 if (g < 7) {
;                     const size_t offn = (size_t)(row0 + ((g + 1) >> 2) * HALF + ((g + 1) & 3) * 16) * D + col0;
; #pragma unroll
;                     for (int bj = 0; bj < 2; ++bj) {
;                         const size_t o = offn + bj * HALF;
;                         if (mode == 5) { xi[nb][2 * bj] = *(const f32x4*)(xin + o); xi[nb][2 * bj + 1] = *(const f32x4*)(xin + o + 4); }
;                         else { xh[nb][bj] = *(const u32x4*)(hin + o); xl[nb][bj] = *(const u32x4*)(lin + o); }
;                         if (mode == 4) pq[nb][bj] = *(const u32x4*)(ob + o);
;                     }
;                 }
;                 float s = 1.f;
;                 if (mode == 4) s = __shfl(ai ? sB : sA, m * 16 + fr);
;                 float ss = 0.f;
; #pragma unroll
;                 for (int bj = 0; bj < 2; ++bj) {
;                     u32x4 wh, wl;
; #pragma unroll
;                     for (int n = 0; n < 2; ++n) {
;                         const int q = 2 * bj + n;
;                         const unsigned h0 = n ? xh[cb][bj].z : xh[cb][bj].x, h1 = n ? xh[cb][bj].w : xh[cb][bj].y, l0 = n ? xl[cb][bj].z : xl[cb][bj].x, l1 = n ? xl[cb][bj].w : xl[cb][bj].y;
;                         f32x4 xo;
;                         if (mode == 5) xo = xi[cb][q];
;                         else { xo[0] = bf_lo(h0) + bf_lo(l0); xo[1] = bf_hi(h0) + bf_hi(l0); xo[2] = bf_lo(h1) + bf_lo(l1); xo[3] = bf_hi(h1) + bf_hi(l1); }
;                         f32x4 v;
;                         if (mode != 4) v = xo + acc[ai][bj][m][n] * alpha + bvv[q];
;                         else {
;                             const f32x4 a = acc[ai][bj][m][n] * s;
;                             const unsigned p0 = n ? pq[cb][bj].z : pq[cb][bj].x, p1 = n ? pq[cb][bj].w : pq[cb][bj].y;
;                             v[0] = xo[0] + sigmoidf_(a[0]) * bf_lo(p0); v[1] = xo[1] + sigmoidf_(a[1]) * bf_hi(p0);
	v_pk_mul_f32 v[126:127], v[126:127], v[200:201] op_sel_hi:[1,0]
	v_cndmask_b32_e64 v131, v205, v131, s[44:45]
	v_lshlrev_b32_e32 v191, 2, v131
	v_xor_b32_e32 v131, 32, v205
	v_mul_f32_e32 v126, 0xbfb8aa3b, v126
	v_cmp_lt_i32_e64 s[44:45], v131, v130
	v_exp_f32_e32 v126, v126
	v_pk_mul_f32 v[128:129], v[128:129], v[200:201] op_sel_hi:[1,0]
	v_cndmask_b32_e64 v130, v205, v131, s[44:45]
	v_lshlrev_b32_e32 v224, 2, v130
	v_lshlrev_b64 v[130:131], 10, v[194:195]
	v_lshl_add_u64 v[130:131], v[130:131], 0, v[188:189]
	v_lshlrev_b64 v[196:197], 1, v[130:131]
	v_add_f32_e32 v126, 1.0, v126
	v_lshl_add_u64 v[130:131], s[34:35], 0, v[196:197]
	v_lshl_add_u64 v[132:133], s[92:93], 0, v[196:197]
	v_lshl_add_u64 v[228:229], s[6:7], 0, v[196:197]
	v_rcp_f32_e32 v126, v126
	global_load_dwordx4 v[150:153], v[130:131], off
	global_load_dwordx4 v[154:157], v[132:133], off
	global_load_dwordx4 v[142:145], v[228:229], off
	global_load_dwordx4 v[134:137], v[130:131], off offset:256
	global_load_dwordx4 v[138:141], v[132:133], off offset:256
	s_nop 0
	global_load_dwordx4 v[130:133], v[228:229], off offset:256
	v_pk_mul_f32 v[122:123], v[122:123], v[200:201] op_sel_hi:[1,0]
	v_pk_mul_f32 v[124:125], v[124:125], v[200:201] op_sel_hi:[1,0]
	v_mul_f32_e32 v122, 0xbfb8aa3b, v122
	v_exp_f32_e32 v122, v122
	v_pk_mul_f32 v[118:119], v[118:119], v[200:201] op_sel_hi:[1,0]
	v_pk_mul_f32 v[120:121], v[120:121], v[200:201] op_sel_hi:[1,0]
	v_mul_f32_e32 v118, 0xbfb8aa3b, v118
	v_add_f32_e32 v122, 1.0, v122
	v_rcp_f32_e32 v122, v122
	v_exp_f32_e32 v118, v118
	v_pk_mul_f32 v[114:115], v[114:115], v[200:201] op_sel_hi:[1,0]
	v_pk_mul_f32 v[116:117], v[116:117], v[200:201] op_sel_hi:[1,0]
	v_mul_f32_e32 v114, 0xbfb8aa3b, v114
	v_add_f32_e32 v118, 1.0, v118
	v_rcp_f32_e32 v118, v118
	v_exp_f32_e32 v114, v114
	s_lshl_b32 s44, s2, 2
	s_ashr_i32 s45, s44, 31
	v_add_f32_e32 v114, 1.0, v114
	v_rcp_f32_e32 v114, v114
	s_waitcnt vmcnt(11)
	v_lshlrev_b32_e32 v227, 16, v170
	s_waitcnt vmcnt(10)
	v_lshlrev_b32_e32 v228, 16, v174
	v_and_b32_e32 v174, 0xffff0000, v174
	v_and_b32_e32 v170, 0xffff0000, v170
	v_add_f32_e32 v227, v228, v227
	v_add_f32_e32 v170, v174, v170
	v_lshlrev_b32_e32 v174, 16, v171
	v_lshlrev_b32_e32 v228, 16, v175
	v_and_b32_e32 v175, 0xffff0000, v175
	v_and_b32_e32 v171, 0xffff0000, v171
	v_add_f32_e32 v171, v175, v171
	s_waitcnt vmcnt(9)
	v_lshlrev_b32_e32 v175, 16, v166
	v_fmac_f32_e32 v227, v126, v175
	v_mul_f32_e32 v126, 0xbfb8aa3b, v127
	v_exp_f32_e32 v126, v126
	v_and_b32_e32 v127, 0xffff0000, v166
	v_add_f32_e32 v174, v228, v174
	v_add_f32_e32 v126, 1.0, v126
	v_rcp_f32_e32 v126, v126
	s_nop 0
	v_fmac_f32_e32 v170, v126, v127
	v_mul_f32_e32 v126, 0xbfb8aa3b, v128
	v_exp_f32_e32 v126, v126
	v_lshlrev_b32_e32 v127, 16, v167
	v_add_f32_e32 v126, 1.0, v126
	v_rcp_f32_e32 v126, v126
	s_nop 0
	v_fmac_f32_e32 v174, v126, v127
	v_mul_f32_e32 v126, 0xbfb8aa3b, v129
	v_exp_f32_e32 v126, v126
	v_and_b32_e32 v127, 0xffff0000, v167
	v_add_f32_e32 v126, 1.0, v126
	v_rcp_f32_e32 v126, v126
	s_nop 0
	v_fmac_f32_e32 v171, v126, v127
	v_cvt_pk_bf16_f32 v126, v227, v170
	v_cvt_pk_bf16_f32 v127, v174, v171
	s_nop 0
	v_lshlrev_b32_e32 v128, 16, v126
	v_and_b32_e32 v129, 0xffff0000, v126
	v_sub_f32_e32 v128, v227, v128
	v_sub_f32_e32 v129, v170, v129
	v_cvt_pk_bf16_f32 v166, v128, v129
	v_lshlrev_b32_e32 v128, 16, v127
	v_and_b32_e32 v129, 0xffff0000, v127
	v_sub_f32_e32 v128, v174, v128
	v_sub_f32_e32 v129, v171, v129
	v_cvt_pk_bf16_f32 v167, v128, v129
	v_mul_f32_e32 v128, v170, v170
	v_mul_f32_e32 v129, v171, v171
	v_fmac_f32_e32 v128, v227, v227
	v_fmac_f32_e32 v129, v174, v174
	v_add_f32_e32 v170, v128, v129
	v_lshlrev_b32_e32 v128, 16, v172
	v_lshlrev_b32_e32 v129, 16, v176
	v_add_f32_e32 v171, v129, v128
	v_and_b32_e32 v128, 0xffff0000, v176
	v_and_b32_e32 v129, 0xffff0000, v172
	v_add_f32_e32 v172, v128, v129
	v_lshlrev_b32_e32 v128, 16, v173
	v_lshlrev_b32_e32 v129, 16, v177
	v_add_f32_e32 v174, v129, v128
	v_and_b32_e32 v128, 0xffff0000, v177
	v_and_b32_e32 v129, 0xffff0000, v173
	v_add_f32_e32 v173, v128, v129
	v_lshlrev_b32_e32 v128, 16, v168
	v_fmac_f32_e32 v171, v122, v128
	v_mul_f32_e32 v122, 0xbfb8aa3b, v123
	v_exp_f32_e32 v122, v122
	v_and_b32_e32 v123, 0xffff0000, v168
	v_add_f32_e32 v122, 1.0, v122
	v_rcp_f32_e32 v122, v122
	s_nop 0
	v_fmac_f32_e32 v172, v122, v123
	v_mul_f32_e32 v122, 0xbfb8aa3b, v124
	v_exp_f32_e32 v122, v122
	v_lshlrev_b32_e32 v123, 16, v169
	v_cvt_pk_bf16_f32 v128, v171, v172
	v_add_f32_e32 v122, 1.0, v122
	v_rcp_f32_e32 v122, v122
	s_nop 0
	v_fmac_f32_e32 v174, v122, v123
	v_mul_f32_e32 v122, 0xbfb8aa3b, v125
	v_exp_f32_e32 v122, v122
	v_and_b32_e32 v123, 0xffff0000, v169
	v_lshl_add_u64 v[124:125], s[28:29], 0, v[198:199]
	v_add_f32_e32 v122, 1.0, v122
	v_rcp_f32_e32 v122, v122
	s_nop 0
	v_fmac_f32_e32 v173, v122, v123
	v_lshlrev_b32_e32 v122, 16, v128
	v_and_b32_e32 v123, 0xffff0000, v128
	v_sub_f32_e32 v122, v171, v122
	v_sub_f32_e32 v123, v172, v123
	v_cvt_pk_bf16_f32 v129, v174, v173
	v_cvt_pk_bf16_f32 v168, v122, v123
	s_nop 0
	v_lshlrev_b32_e32 v122, 16, v129
	v_and_b32_e32 v123, 0xffff0000, v129
	v_sub_f32_e32 v122, v174, v122
	v_sub_f32_e32 v123, v173, v123
	v_cvt_pk_bf16_f32 v169, v122, v123
	v_mul_f32_e32 v122, v172, v172
	v_mul_f32_e32 v123, v173, v173
	v_fmac_f32_e32 v122, v171, v171
	v_fmac_f32_e32 v123, v174, v174
	v_add_f32_e32 v122, v122, v123
	v_add_f32_e32 v170, v170, v122
	v_lshl_add_u64 v[122:123], s[10:11], 0, v[198:199]
	global_store_dwordx4 v[122:123], v[126:129], off
	global_store_dwordx4 v[124:125], v[166:169], off
	s_waitcnt vmcnt(10)
; __device__ __forceinline__ float bf_lo(unsigned w) { return __uint_as_float(w << 16); }
; __device__ __forceinline__ float bf_hi(unsigned w) { return __uint_as_float(w & 0xffff0000u); }
;     template <int mode> __device__ __forceinline__ void run(const f32x4 (&acc)[2][2][4][2], const Unit& u, int wr, int wc, int fr, int fq, const LAS float* sc) const {
;     ...
;                 for (int bj = 0; bj < 2; ++bj) {
;                     u32x4 wh, wl;
; #pragma unroll
;                     for (int n = 0; n < 2; ++n) {
;                         const int q = 2 * bj + n;
;                         const unsigned h0 = n ? xh[cb][bj].z : xh[cb][bj].x, h1 = n ? xh[cb][bj].w : xh[cb][bj].y, l0 = n ? xl[cb][bj].z : xl[cb][bj].x, l1 = n ? xl[cb][bj].w : xl[cb][bj].y;
;                         f32x4 xo;
;                         if (mode == 5) xo = xi[cb][q];
;                         else { xo[0] = bf_lo(h0) + bf_lo(l0); xo[1] = bf_hi(h0) + bf_hi(l0); xo[2] = bf_lo(h1) + bf_lo(l1); xo[3] = bf_hi(h1) + bf_hi(l1); }
;                         f32x4 v;
;                         if (mode != 4) v = xo + acc[ai][bj][m][n] * alpha + bvv[q];
;                         else {
;                             const f32x4 a = acc[ai][bj][m][n] * s;
;                             const unsigned p0 = n ? pq[cb][bj].z : pq[cb][bj].x, p1 = n ? pq[cb][bj].w : pq[cb][bj].y;
;                             v[0] = xo[0] + sigmoidf_(a[0]) * bf_lo(p0); v[1] = xo[1] + sigmoidf_(a[1]) * bf_hi(p0);
;                             v[2] = xo[2] + sigmoidf_(a[2]) * bf_lo(p1); v[3] = xo[3] + sigmoidf_(a[3]) * bf_hi(p1);
;                         }
;                         const unsigned w0 = pk2(v[0], v[1]), w1 = pk2(v[2], v[3]);
;                         const unsigned m0 = pk2(v[0] - bf_lo(w0), v[1] - bf_hi(w0)), m1 = pk2(v[2] - bf_lo(w1), v[3] - bf_hi(w1));
;                         if (n == 0) { wh.x = w0; wh.y = w1; wl.x = m0; wl.y = m1; } else { wh.z = w0; wh.w = w1; wl.z = m0; wl.w = m1; }
;                         ss += (v[0] * v[0] + v[1] * v[1]) + (v[2] * v[2] + v[3] * v[3]);
;                     }
;                     *(u32x4*)(xb + off + bj * HALF) = wh;
;                     *(u32x4*)(lout + off + bj * HALF) = wl;
;                 }
;                 ss += __shfl_xor(ss, 16); ss += __shfl_xor(ss, 32);
;                 if (fq == 0) ssq_out[(size_t)row * 16 + u.pn * 4 + wc] = ss;
	v_lshlrev_b32_e32 v126, 16, v158
	s_waitcnt vmcnt(9)
	v_lshlrev_b32_e32 v127, 16, v162
	v_add_f32_e32 v128, v127, v126
	v_and_b32_e32 v126, 0xffff0000, v162
	v_and_b32_e32 v127, 0xffff0000, v158
	v_add_f32_e32 v129, v126, v127
	v_lshlrev_b32_e32 v126, 16, v159
	v_lshlrev_b32_e32 v127, 16, v163
	v_add_f32_e32 v158, v127, v126
	v_and_b32_e32 v126, 0xffff0000, v163
	v_and_b32_e32 v127, 0xffff0000, v159
	v_add_f32_e32 v159, v126, v127
	s_waitcnt vmcnt(8)
	v_lshlrev_b32_e32 v126, 16, v146
	v_fmac_f32_e32 v128, v118, v126
	v_mul_f32_e32 v118, 0xbfb8aa3b, v119
	v_exp_f32_e32 v118, v118
	v_and_b32_e32 v119, 0xffff0000, v146
	v_add_f32_e32 v118, 1.0, v118
	v_rcp_f32_e32 v118, v118
	s_nop 0
	v_fmac_f32_e32 v129, v118, v119
	v_mul_f32_e32 v118, 0xbfb8aa3b, v120
	v_exp_f32_e32 v118, v118
	v_lshlrev_b32_e32 v119, 16, v147
	v_add_f32_e32 v118, 1.0, v118
	v_rcp_f32_e32 v118, v118
	s_nop 0
	v_fmac_f32_e32 v158, v118, v119
	v_mul_f32_e32 v118, 0xbfb8aa3b, v121
	v_exp_f32_e32 v118, v118
	v_and_b32_e32 v119, 0xffff0000, v147
	v_add_f32_e32 v118, 1.0, v118
	v_rcp_f32_e32 v118, v118
	s_nop 0
	v_fmac_f32_e32 v159, v118, v119
	v_cvt_pk_bf16_f32 v118, v128, v129
	v_cvt_pk_bf16_f32 v119, v158, v159
	s_nop 0
	v_lshlrev_b32_e32 v120, 16, v118
	v_and_b32_e32 v121, 0xffff0000, v118
	v_sub_f32_e32 v120, v128, v120
	v_sub_f32_e32 v121, v129, v121
	v_cvt_pk_bf16_f32 v126, v120, v121
	v_lshlrev_b32_e32 v120, 16, v119
	v_and_b32_e32 v121, 0xffff0000, v119
	v_sub_f32_e32 v120, v158, v120
	v_sub_f32_e32 v121, v159, v121
	v_cvt_pk_bf16_f32 v127, v120, v121
	v_mul_f32_e32 v120, v129, v129
	v_mul_f32_e32 v121, v159, v159
	v_fmac_f32_e32 v120, v128, v128
	v_fmac_f32_e32 v121, v158, v158
	v_add_f32_e32 v120, v120, v121
	v_add_f32_e32 v146, v120, v170
	v_lshlrev_b32_e32 v120, 16, v160
	v_lshlrev_b32_e32 v121, 16, v164
	v_add_f32_e32 v147, v121, v120
	v_and_b32_e32 v120, 0xffff0000, v164
	v_and_b32_e32 v121, 0xffff0000, v160
	v_add_f32_e32 v158, v120, v121
	v_lshlrev_b32_e32 v120, 16, v161
	v_lshlrev_b32_e32 v121, 16, v165
	v_add_f32_e32 v159, v121, v120
	v_and_b32_e32 v120, 0xffff0000, v165
	v_and_b32_e32 v121, 0xffff0000, v161
	v_add_f32_e32 v160, v120, v121
	v_lshlrev_b32_e32 v120, 16, v148
	v_fmac_f32_e32 v147, v114, v120
	v_mul_f32_e32 v114, 0xbfb8aa3b, v115
	v_exp_f32_e32 v114, v114
	v_and_b32_e32 v115, 0xffff0000, v148
	v_add_f32_e32 v114, 1.0, v114
	v_rcp_f32_e32 v114, v114
	s_nop 0
	v_fmac_f32_e32 v158, v114, v115
	v_mul_f32_e32 v114, 0xbfb8aa3b, v116
	v_exp_f32_e32 v114, v114
	v_lshlrev_b32_e32 v115, 16, v149
	v_cvt_pk_bf16_f32 v120, v147, v158
	v_add_f32_e32 v114, 1.0, v114
	v_rcp_f32_e32 v114, v114
	s_nop 0
	v_fmac_f32_e32 v159, v114, v115
	v_mul_f32_e32 v114, 0xbfb8aa3b, v117
	v_exp_f32_e32 v114, v114
	v_and_b32_e32 v115, 0xffff0000, v149
	v_add_f32_e32 v114, 1.0, v114
	v_rcp_f32_e32 v114, v114
	s_nop 0
	v_fmac_f32_e32 v160, v114, v115
	v_lshlrev_b32_e32 v114, 16, v120
	v_and_b32_e32 v115, 0xffff0000, v120
	v_sub_f32_e32 v114, v147, v114
	v_sub_f32_e32 v115, v158, v115
	v_cvt_pk_bf16_f32 v121, v159, v160
	v_cvt_pk_bf16_f32 v128, v114, v115
	s_nop 0
	v_lshlrev_b32_e32 v114, 16, v121
	v_and_b32_e32 v115, 0xffff0000, v121
	v_sub_f32_e32 v114, v159, v114
	v_sub_f32_e32 v115, v160, v115
	v_cvt_pk_bf16_f32 v129, v114, v115
	v_mul_f32_e32 v114, v158, v158
	v_mul_f32_e32 v115, v160, v160
	v_fmac_f32_e32 v114, v147, v147
	v_fmac_f32_e32 v115, v159, v159
	v_add_f32_e32 v114, v114, v115
	v_add_f32_e32 v114, v114, v146
	ds_bpermute_b32 v115, v191, v114
	global_store_dwordx4 v[122:123], v[118:121], off offset:256
	global_store_dwordx4 v[124:125], v[126:129], off offset:256
	s_waitcnt lgkmcnt(0)
	v_add_f32_e32 v114, v114, v115
	ds_bpermute_b32 v115, v224, v114
	s_and_saveexec_b64 s[4:5], s[40:41]
	s_cbranch_execz .LBB0_162
	v_lshlrev_b64 v[116:117], 6, v[192:193]
	v_lshl_add_u64 v[116:117], s[62:63], 0, v[116:117]
	v_lshl_add_u64 v[116:117], s[44:45], 2, v[116:117]
	s_lshl_b32 s24, s20, 2
	v_lshl_add_u64 v[116:117], v[116:117], 0, s[24:25]
	s_waitcnt lgkmcnt(0)
	v_add_f32_e32 v114, v114, v115
	global_store_dword v[116:117], v114, off

; #define PG8_STAGE(bufoff, gbase, voff) do { _Pragma("unroll") for (int _i = 0; _i < 2; ++_i) \
;         __builtin_amdgcn_global_load_lds((const unsigned*)((const char*)(gbase) + (voff)[_i]), (LAS unsigned*)(lds + (bufoff) + ldsw + _i * 8192), 16, 0, 0); } while (0)
; #define PG8_WAIT_V(n) asm volatile("s_waitcnt vmcnt(" #n ")" ::: "memory")
; #define PG8_BAR __builtin_amdgcn_s_barrier()
; template <int MODE, class EpiT, class Sched>
; __device__ __forceinline__ void gemm_phase(LAS unsigned char* lds, const Gemm g, const Sched& S, const EpiT& E) {
;     ...
;     f32x4 acc[2][2][4][2];
; #pragma unroll
;     for (int a = 0; a < 2; ++a)
; #pragma unroll
;         for (int b = 0; b < 2; ++b)
; #pragma unroll
;             for (int m = 0; m < 4; ++m)
; #pragma unroll
;                 for (int n = 0; n < 2; ++n) acc[a][b][m][n] = (f32x4){0.f, 0.f, 0.f, 0.f};
;     bf16x8 At[4][2], B0[2][2], B1[2][2];
;     const char* cA = (const char*)g.A + (size_t)cur.pm * tstep; const char* cB = (const char*)g.Bt + (size_t)cur.pn * tstep;
;     PG8_STAGE(PG8_SB(0, 0), cB, voffB); PG8_STAGE(PG8_SA(0, 0), cA, voffA); PG8_STAGE(PG8_SB(0, 1), cB + hstep, voffB); PG8_STAGE(PG8_SA(0, 1), cA + hstep, voffA);
;     if (wr == 1) PG8_BAR;
;     PG8_WAIT_V(4); PG8_BAR;
;     PG8_STAGE(PG8_SB(1, 0), cB + kstep, voffB); PG8_STAGE(PG8_SA(1, 0), cA + kstep, voffA); PG8_STAGE(PG8_SB(1, 1), cB + hstep + kstep, voffB);
;     PG8_WAIT_V(6); PG8_BAR;
.LBB0_271:
	s_add_i32 m0, s30, 0x18000
	v_lshl_add_u64 v[2:3], v[2:3], 0, s[76:77]
	s_waitcnt vmcnt(4)
	s_barrier
	global_load_lds_dwordx4 v[2:3], off
	v_lshl_add_u64 v[2:3], v[4:5], 0, s[76:77]
	s_add_i32 m0, s30, 0x1a000
	s_add_i32 s56, s30, 0x8000
	global_load_lds_dwordx4 v[2:3], off
	v_lshl_add_u64 v[2:3], v[6:7], 0, s[76:77]
	s_mov_b32 m0, s56
	s_add_i32 s57, s30, 0xa000
	global_load_lds_dwordx4 v[2:3], off
	v_lshl_add_u64 v[2:3], v[8:9], 0, s[76:77]
	s_mov_b32 m0, s57
	v_lshrrev_b32_e32 v21, 1, v50
	global_load_lds_dwordx4 v[2:3], off
	s_add_i32 m0, s30, 0x1c000
	v_lshl_add_u64 v[2:3], v[10:11], 0, s[76:77]
	global_load_lds_dwordx4 v[2:3], off
	v_lshl_add_u64 v[2:3], v[12:13], 0, s[76:77]
	s_add_i32 m0, s30, 0x1e000
	v_and_b32_e32 v21, 24, v21
	global_load_lds_dwordx4 v[2:3], off
	v_and_b32_e32 v20, 15, v50
	v_lshlrev_b32_e32 v22, 1, v21
	v_lshl_or_b32 v156, s29, 6, v20
	v_lshl_or_b32 v22, v20, 6, v22
	v_lshlrev_b32_e32 v20, 2, v20
	s_lshl_b32 s34, s29, 13
	v_and_b32_e32 v23, 32, v20
	s_lshl_b32 s28, s28, 5
	v_bitop3_b32 v24, v22, s34, v23 bitop3:0xde
	s_and_b32 s34, s28, 0x60
	s_lshl_b32 s28, s34, 7
	v_bitop3_b32 v157, v22, s28, v23 bitop3:0xde
	v_add_u32_e32 v250, 0x10000, v157
	s_lshl_b32 s28, s29, 8
	v_cvt_u32_f32_e32 v2, v51
	s_lshr_b32 s55, s16, 6
	s_add_i32 s28, s28, 0
	s_add_i32 s28, s28, 0x20000
	s_add_i32 s60, s55, -2
	s_cmp_lg_u64 s[12:13], 0
	v_add_u32_e32 v158, s28, v20
	s_cselect_b64 s[28:29], -1, 0
	v_or_b32_e32 v159, s34, v21
	s_sub_i32 s34, 0, s20
	v_readfirstlane_b32 s35, v2
	s_mul_i32 s34, s34, s35
	s_mul_hi_u32 s34, s35, s34
	s_add_i32 s61, s35, s34
	s_add_u32 s34, s22, 0x80
	v_add_u32_e32 v2, v16, v14
	s_addc_u32 s35, 0, 0
	v_add_lshl_u32 v2, v2, v15, 1
	v_mov_b32_e32 v3, v1
	v_lshl_add_u64 v[148:149], s[34:35], 0, v[2:3]
	v_add_u32_e32 v2, v19, v17
	s_waitcnt vmcnt(6)
	v_add_lshl_u32 v2, v2, v18, 1
	v_lshl_add_u64 v[150:151], s[34:35], 0, v[2:3]
	v_mov_b32_e32 v2, 0
	s_mov_b32 s62, 0
	v_add_u32_e32 v160, 0, v24
	v_mov_b32_e32 v3, v2
	v_mov_b32_e32 v4, v2
	v_mov_b32_e32 v5, v2
	v_mov_b32_e32 v6, v2
	v_mov_b32_e32 v7, v2
	v_mov_b32_e32 v8, v2
	v_mov_b32_e32 v9, v2
	v_mov_b32_e32 v10, v2
	v_mov_b32_e32 v11, v2
	v_mov_b32_e32 v12, v2
	v_mov_b32_e32 v13, v2
	v_mov_b32_e32 v14, v2
	v_mov_b32_e32 v15, v2
	v_mov_b32_e32 v16, v2
	v_mov_b32_e32 v17, v2
	v_mov_b32_e32 v18, v2
	v_mov_b32_e32 v19, v2
	v_mov_b32_e32 v20, v2
	v_mov_b32_e32 v21, v2
	v_mov_b32_e32 v22, v2
	v_mov_b32_e32 v23, v2
	v_mov_b32_e32 v24, v2
	v_mov_b32_e32 v25, v2
	v_mov_b32_e32 v26, v2
	v_mov_b32_e32 v27, v2
	v_mov_b32_e32 v28, v2
	v_mov_b32_e32 v29, v2
	v_mov_b32_e32 v30, v2
	v_mov_b32_e32 v31, v2
	v_mov_b32_e32 v32, v2
	v_mov_b32_e32 v33, v2
	v_mov_b32_e32 v34, v2
	v_mov_b32_e32 v35, v2
	v_mov_b32_e32 v36, v2
	v_mov_b32_e32 v37, v2
	v_mov_b32_e32 v38, v2
	v_mov_b32_e32 v39, v2
	v_mov_b32_e32 v40, v2
	v_mov_b32_e32 v41, v2
	v_mov_b32_e32 v42, v2
	v_mov_b32_e32 v43, v2
	v_mov_b32_e32 v44, v2
	v_mov_b32_e32 v45, v2
	v_mov_b32_e32 v46, v2
	v_mov_b32_e32 v47, v2
	v_mov_b32_e32 v48, v2
	v_mov_b32_e32 v49, v2
	v_mov_b32_e32 v50, v2
	v_mov_b32_e32 v51, v2
	v_mov_b32_e32 v52, v2
	v_mov_b32_e32 v53, v2
	v_mov_b32_e32 v54, v2
	v_mov_b32_e32 v55, v2
	v_mov_b32_e32 v56, v2
	v_mov_b32_e32 v57, v2
	v_mov_b32_e32 v58, v2
	v_mov_b32_e32 v59, v2
	v_mov_b32_e32 v60, v2
	v_mov_b32_e32 v61, v2
	v_mov_b32_e32 v62, v2
	v_mov_b32_e32 v63, v2
	v_mov_b32_e32 v64, v2
	v_mov_b32_e32 v65, v2
	v_mov_b32_e32 v66, v2
	v_mov_b32_e32 v67, v2
	v_mov_b32_e32 v68, v2
	v_mov_b32_e32 v69, v2
	v_mov_b32_e32 v70, v2
	v_mov_b32_e32 v71, v2
	v_mov_b32_e32 v72, v2
	v_mov_b32_e32 v73, v2
	v_mov_b32_e32 v74, v2
	v_mov_b32_e32 v75, v2
	v_mov_b32_e32 v76, v2
	v_mov_b32_e32 v77, v2
	v_mov_b32_e32 v78, v2
	v_mov_b32_e32 v79, v2
	v_mov_b32_e32 v80, v2
	v_mov_b32_e32 v81, v2
	v_mov_b32_e32 v82, v2
	v_mov_b32_e32 v83, v2
	v_mov_b32_e32 v84, v2
	v_mov_b32_e32 v85, v2
	v_mov_b32_e32 v86, v2
	v_mov_b32_e32 v87, v2
	v_mov_b32_e32 v88, v2
	v_mov_b32_e32 v89, v2
	v_mov_b32_e32 v90, v2
	v_mov_b32_e32 v91, v2
	v_mov_b32_e32 v92, v2
	v_mov_b32_e32 v93, v2
	v_mov_b32_e32 v94, v2
	v_mov_b32_e32 v95, v2
	v_mov_b32_e32 v96, v2
	v_mov_b32_e32 v97, v2
	v_mov_b32_e32 v98, v2
	v_mov_b32_e32 v99, v2
	v_mov_b32_e32 v100, v2
	v_mov_b32_e32 v101, v2
	v_mov_b32_e32 v102, v2
	v_mov_b32_e32 v103, v2
	v_mov_b32_e32 v104, v2
	v_mov_b32_e32 v105, v2
	v_mov_b32_e32 v106, v2
	v_mov_b32_e32 v107, v2
	v_mov_b32_e32 v108, v2
	v_mov_b32_e32 v109, v2
	v_mov_b32_e32 v110, v2
	v_mov_b32_e32 v111, v2
	v_mov_b32_e32 v112, v2
	v_mov_b32_e32 v113, v2
	v_mov_b32_e32 v114, v2
	v_mov_b32_e32 v115, v2
	v_mov_b32_e32 v116, v2
	v_mov_b32_e32 v117, v2
	v_mov_b32_e32 v118, v2
	v_mov_b32_e32 v119, v2
	v_mov_b32_e32 v120, v2
	v_mov_b32_e32 v121, v2
	v_mov_b32_e32 v122, v2
	v_mov_b32_e32 v123, v2
	v_mov_b32_e32 v124, v2
	v_mov_b32_e32 v125, v2
	v_mov_b32_e32 v126, v2
	v_mov_b32_e32 v127, v2
	v_mov_b32_e32 v128, v2
	v_mov_b32_e32 v129, v2
	s_barrier
	s_branch .LBB0_273

; #define PG8_STAGE(bufoff, gbase, voff) do { _Pragma("unroll") for (int _i = 0; _i < 2; ++_i) \
;         __builtin_amdgcn_global_load_lds((const unsigned*)((const char*)(gbase) + (voff)[_i]), (LAS unsigned*)(lds + (bufoff) + ldsw + _i * 8192), 16, 0, 0); } while (0)
; #define PG8_LDA(dst, b, h) do { _Pragma("unroll") for (int m = 0; m < 4; ++m) _Pragma("unroll") for (int k = 0; k < 2; ++k) dst[m][k] = *(const LAS bf16x8*)(lds + PG8_SA(b, h) + aoff + m * 2048 + k * 1024); } while (0)
; #define PG8_LDB(dst, b, h) do { _Pragma("unroll") for (int n = 0; n < 2; ++n) _Pragma("unroll") for (int k = 0; k < 2; ++k) dst[n][k] = *(const LAS bf16x8*)(lds + PG8_SB(b, h) + boff + n * 2048 + k * 1024); } while (0)
; #define PG8_MMA(ai, bj, At, Bt) do { __builtin_amdgcn_s_setprio(1); _Pragma("unroll") for (int m = 0; m < 4; ++m) _Pragma("unroll") for (int n = 0; n < 2; ++n) _Pragma("unroll") for (int k = 0; k < 2; ++k) \
;         acc[ai][bj][m][n] = __builtin_amdgcn_mfma_f32_16x16x32_bf16(Bt[n][k], At[m][k], acc[ai][bj][m][n], 0, 0, 0); __builtin_amdgcn_s_setprio(0); } while (0)
; #define PG8_WAIT_V(n) asm volatile("s_waitcnt vmcnt(" #n ")" ::: "memory")
; #define PG8_WAIT_L(n) asm volatile("s_waitcnt lgkmcnt(" #n ")" ::: "memory")
; template <int MODE, class EpiT, class Sched>
; __device__ __forceinline__ void gemm_phase(LAS unsigned char* lds, const Gemm g, const Sched& S, const EpiT& E) {
;     ...
;         for (int t = 0; t < nt; t += 2) {
;             const bool last = (t == nt - 2);
;             const char* a1 = cA + (size_t)(t + 1) * kstep;
;             const char* a2 = last ? nA : cA + (size_t)(t + 2) * kstep; const char* b2 = last ? nB : cB + (size_t)(t + 2) * kstep;
;             const char* a3 = a2 + kstep; const char* b3 = b2 + kstep;
;             PG8_LDB(B0, 0, 0); PG8_SCHED; PG8_LDA(At, 0, 0); PG8_STAGE(PG8_SA(1, 1), a1 + hstep, voffA);
;             PG8_WAIT_L(8); PG8_BAR; PG8_WAIT_L(0); PG8_MMA(0, 0, At, B0); PG8_BAR; PG8_SCHED;
;             PG8_LDB(B1, 0, 1); PG8_STAGE(PG8_SB(0, 0), b2, voffB);
;             PG8_BAR; PG8_WAIT_L(0); PG8_MMA(0, 1, At, B1); PG8_BAR;
;             PG8_LDA(At, 0, 1); PG8_STAGE(PG8_SA(0, 0), a2, voffA);
;             PG8_BAR; PG8_WAIT_L(0); PG8_MMA(1, 0, At, B0); PG8_BAR; PG8_SCHED;
;             PG8_STAGE(PG8_SB(0, 1), b2 + hstep, voffB);
;             PG8_WAIT_V(6); PG8_BAR; PG8_MMA(1, 1, At, B1); PG8_BAR;
.LBB0_280:
	s_add_i32 s68, s46, 2
	s_add_u32 s52, s10, s44
	s_addc_u32 s47, s11, s45
	s_add_u32 s58, s4, s44
	s_addc_u32 s53, s5, s45
	s_add_u32 s100, s10, s44
	s_addc_u32 s101, s11, s45
	s_add_u32 s100, s100, s22
	s_addc_u32 s101, s101, 0
	s_sub_u32 s100, s100, 0x80
	s_subb_u32 s101, s101, 0
	s_add_i32 s59, 0, 0x10000
	ds_read_b128 v[134:137], v250
	ds_read_b128 v[138:141], v250 offset:1024
	ds_read_b128 v[142:145], v250 offset:2048
	ds_read_b128 v[152:155], v250 offset:3072
	s_cmp_eq_u32 s60, s46
	s_cselect_b32 s46, s34, s52
	s_cselect_b32 s47, s35, s47
	s_cselect_b32 s53, s39, s53
	s_cselect_b32 s52, s38, s58
	s_add_i32 m0, s30, 0xc000
	ds_read_b128 v[162:165], v160
	ds_read_b128 v[166:169], v160 offset:1024
	ds_read_b128 v[170:173], v160 offset:2048
	ds_read_b128 v[174:177], v160 offset:3072
	ds_read_b128 v[182:185], v160 offset:4096
	ds_read_b128 v[186:189], v160 offset:5120
	ds_read_b128 v[190:193], v160 offset:6144
	ds_read_b128 v[194:197], v160 offset:7168
	global_load_lds_dwordx4 v0, s[100:101]
	s_add_i32 m0, s30, 0xe000
	s_nop 0
	global_load_lds_dwordx4 v146, s[100:101]
	s_waitcnt lgkmcnt(8)
	s_barrier
	s_waitcnt lgkmcnt(0)
	v_mfma_f32_16x16x32_bf16 v[126:129], v[134:137], v[162:165], v[126:129]
	v_mfma_f32_16x16x32_bf16 v[122:125], v[142:145], v[162:165], v[122:125]
	v_mfma_f32_16x16x32_bf16 v[118:121], v[134:137], v[170:173], v[118:121]
	v_mfma_f32_16x16x32_bf16 v[114:117], v[142:145], v[170:173], v[114:117]
	v_mfma_f32_16x16x32_bf16 v[110:113], v[134:137], v[182:185], v[110:113]
	v_mfma_f32_16x16x32_bf16 v[106:109], v[142:145], v[182:185], v[106:109]
	v_mfma_f32_16x16x32_bf16 v[102:105], v[134:137], v[190:193], v[102:105]
	v_mfma_f32_16x16x32_bf16 v[98:101], v[142:145], v[190:193], v[98:101]
	v_mfma_f32_16x16x32_bf16 v[126:129], v[138:141], v[166:169], v[126:129]
	v_mfma_f32_16x16x32_bf16 v[122:125], v[152:155], v[166:169], v[122:125]
	v_mfma_f32_16x16x32_bf16 v[118:121], v[138:141], v[174:177], v[118:121]
	v_mfma_f32_16x16x32_bf16 v[114:117], v[152:155], v[174:177], v[114:117]
	v_mfma_f32_16x16x32_bf16 v[110:113], v[138:141], v[186:189], v[110:113]
	v_mfma_f32_16x16x32_bf16 v[106:109], v[152:155], v[186:189], v[106:109]
	v_mfma_f32_16x16x32_bf16 v[102:105], v[138:141], v[194:197], v[102:105]
	v_mfma_f32_16x16x32_bf16 v[98:101], v[152:155], v[194:197], v[98:101]
	s_barrier
	s_add_i32 s58, 0, 0x14000
	s_add_i32 s59, s59, s24
	s_add_u32 s98, s52, 0x80
	s_addc_u32 s99, s53, 0
	s_mov_b32 m0, s59
	ds_read_b128 v[220:223], v250 offset:16384
	ds_read_b128 v[224:227], v250 offset:17408
	ds_read_b128 v[228:231], v250 offset:18432
	ds_read_b128 v[232:235], v250 offset:19456
	global_load_lds_dwordx4 v0, s[52:53]
	s_add_i32 m0, s59, 0x2000
	s_nop 0
	global_load_lds_dwordx4 v146, s[52:53]
	s_barrier
	s_waitcnt lgkmcnt(0)
	v_mfma_f32_16x16x32_bf16 v[94:97], v[220:223], v[162:165], v[94:97]
	v_mfma_f32_16x16x32_bf16 v[90:93], v[228:231], v[162:165], v[90:93]
	v_mfma_f32_16x16x32_bf16 v[86:89], v[220:223], v[170:173], v[86:89]
	v_mfma_f32_16x16x32_bf16 v[82:85], v[228:231], v[170:173], v[82:85]
	v_mfma_f32_16x16x32_bf16 v[78:81], v[220:223], v[182:185], v[78:81]
	v_mfma_f32_16x16x32_bf16 v[74:77], v[228:231], v[182:185], v[74:77]
	v_mfma_f32_16x16x32_bf16 v[70:73], v[220:223], v[190:193], v[70:73]
	v_mfma_f32_16x16x32_bf16 v[66:69], v[228:231], v[190:193], v[66:69]
	v_mfma_f32_16x16x32_bf16 v[94:97], v[224:227], v[166:169], v[94:97]
	v_mfma_f32_16x16x32_bf16 v[90:93], v[232:235], v[166:169], v[90:93]
	v_mfma_f32_16x16x32_bf16 v[86:89], v[224:227], v[174:177], v[86:89]
	v_mfma_f32_16x16x32_bf16 v[82:85], v[232:235], v[174:177], v[82:85]
	v_mfma_f32_16x16x32_bf16 v[78:81], v[224:227], v[186:189], v[78:81]
	v_mfma_f32_16x16x32_bf16 v[74:77], v[232:235], v[186:189], v[74:77]
	v_mfma_f32_16x16x32_bf16 v[70:73], v[224:227], v[194:197], v[70:73]
	v_mfma_f32_16x16x32_bf16 v[66:69], v[232:235], v[194:197], v[66:69]
	s_barrier
	s_mov_b32 m0, s30
	s_add_u32 s100, s46, 0x80
	s_addc_u32 s101, s47, 0
	ds_read_b128 v[162:165], v160 offset:16384
	ds_read_b128 v[166:169], v160 offset:17408
	ds_read_b128 v[170:173], v160 offset:18432
	ds_read_b128 v[174:177], v160 offset:19456
	ds_read_b128 v[182:185], v160 offset:20480
	ds_read_b128 v[186:189], v160 offset:21504
	ds_read_b128 v[190:193], v160 offset:22528
	ds_read_b128 v[194:197], v160 offset:23552
	global_load_lds_dwordx4 v0, s[46:47]
	s_mov_b32 m0, s50
	s_nop 0
	global_load_lds_dwordx4 v146, s[46:47]
	s_barrier
	s_waitcnt lgkmcnt(0)
	v_mfma_f32_16x16x32_bf16 v[62:65], v[134:137], v[162:165], v[62:65]
	v_mfma_f32_16x16x32_bf16 v[58:61], v[142:145], v[162:165], v[58:61]
	v_mfma_f32_16x16x32_bf16 v[54:57], v[134:137], v[170:173], v[54:57]
	v_mfma_f32_16x16x32_bf16 v[50:53], v[142:145], v[170:173], v[50:53]
	v_mfma_f32_16x16x32_bf16 v[46:49], v[134:137], v[182:185], v[46:49]
	v_mfma_f32_16x16x32_bf16 v[42:45], v[142:145], v[182:185], v[42:45]
	v_mfma_f32_16x16x32_bf16 v[38:41], v[134:137], v[190:193], v[38:41]
	v_mfma_f32_16x16x32_bf16 v[34:37], v[142:145], v[190:193], v[34:37]
	v_mfma_f32_16x16x32_bf16 v[62:65], v[138:141], v[166:169], v[62:65]
	v_mfma_f32_16x16x32_bf16 v[58:61], v[152:155], v[166:169], v[58:61]
	v_mfma_f32_16x16x32_bf16 v[54:57], v[138:141], v[174:177], v[54:57]
	v_mfma_f32_16x16x32_bf16 v[50:53], v[152:155], v[174:177], v[50:53]
	v_mfma_f32_16x16x32_bf16 v[46:49], v[138:141], v[186:189], v[46:49]
	v_mfma_f32_16x16x32_bf16 v[42:45], v[152:155], v[186:189], v[42:45]
	v_mfma_f32_16x16x32_bf16 v[38:41], v[138:141], v[194:197], v[38:41]
	v_mfma_f32_16x16x32_bf16 v[34:37], v[152:155], v[194:197], v[34:37]
	s_barrier
; #define PG8_STAGE(bufoff, gbase, voff) do { _Pragma("unroll") for (int _i = 0; _i < 2; ++_i) \
;         __builtin_amdgcn_global_load_lds((const unsigned*)((const char*)(gbase) + (voff)[_i]), (LAS unsigned*)(lds + (bufoff) + ldsw + _i * 8192), 16, 0, 0); } while (0)
; #define PG8_LDA(dst, b, h) do { _Pragma("unroll") for (int m = 0; m < 4; ++m) _Pragma("unroll") for (int k = 0; k < 2; ++k) dst[m][k] = *(const LAS bf16x8*)(lds + PG8_SA(b, h) + aoff + m * 2048 + k * 1024); } while (0)
; #define PG8_LDB(dst, b, h) do { _Pragma("unroll") for (int n = 0; n < 2; ++n) _Pragma("unroll") for (int k = 0; k < 2; ++k) dst[n][k] = *(const LAS bf16x8*)(lds + PG8_SB(b, h) + boff + n * 2048 + k * 1024); } while (0)
; #define PG8_MMA(ai, bj, At, Bt) do { __builtin_amdgcn_s_setprio(1); _Pragma("unroll") for (int m = 0; m < 4; ++m) _Pragma("unroll") for (int n = 0; n < 2; ++n) _Pragma("unroll") for (int k = 0; k < 2; ++k) \
;         acc[ai][bj][m][n] = __builtin_amdgcn_mfma_f32_16x16x32_bf16(Bt[n][k], At[m][k], acc[ai][bj][m][n], 0, 0, 0); __builtin_amdgcn_s_setprio(0); } while (0)
; #define PG8_WAIT_V(n) asm volatile("s_waitcnt vmcnt(" #n ")" ::: "memory")
; #define PG8_WAIT_L(n) asm volatile("s_waitcnt lgkmcnt(" #n ")" ::: "memory")
; #define PG8_BAR __builtin_amdgcn_s_barrier()
; #define PG8_SCHED __builtin_amdgcn_sched_barrier(0)
; template <int MODE, class EpiT, class Sched>
; __device__ __forceinline__ void gemm_phase(LAS unsigned char* lds, const Gemm g, const Sched& S, const EpiT& E) {
;     ...
;             PG8_WAIT_V(6); PG8_BAR; PG8_MMA(1, 1, At, B1); PG8_BAR;
;             PG8_LDB(B0, 1, 0); PG8_SCHED; PG8_LDA(At, 1, 0); PG8_STAGE(PG8_SA(0, 1), a2 + hstep, voffA);
;             PG8_WAIT_L(8); PG8_BAR; PG8_WAIT_L(0); PG8_MMA(0, 0, At, B0); PG8_BAR; PG8_SCHED;
;             PG8_LDB(B1, 1, 1); PG8_STAGE(PG8_SB(1, 0), b3, voffB);
;             PG8_BAR; PG8_WAIT_L(0); PG8_MMA(0, 1, At, B1); PG8_BAR;
;             PG8_LDA(At, 1, 1); PG8_STAGE(PG8_SA(1, 0), a3, voffA);
;             PG8_BAR; PG8_WAIT_L(0); PG8_MMA(1, 0, At, B0); PG8_BAR; PG8_SCHED;
	s_add_u32 s52, s52, s22
	s_addc_u32 s53, s53, 0
	s_add_i32 s58, s58, s24
	s_mov_b32 m0, s58
	s_nop 0
	global_load_lds_dwordx4 v0, s[52:53]
	s_add_i32 m0, s58, 0x2000
	s_nop 0
	global_load_lds_dwordx4 v146, s[52:53]
	s_waitcnt vmcnt(6)
	s_barrier
	v_mfma_f32_16x16x32_bf16 v[30:33], v[220:223], v[162:165], v[30:33]
	v_mfma_f32_16x16x32_bf16 v[26:29], v[228:231], v[162:165], v[26:29]
	v_mfma_f32_16x16x32_bf16 v[22:25], v[220:223], v[170:173], v[22:25]
	v_mfma_f32_16x16x32_bf16 v[18:21], v[228:231], v[170:173], v[18:21]
	v_mfma_f32_16x16x32_bf16 v[14:17], v[220:223], v[182:185], v[14:17]
	v_mfma_f32_16x16x32_bf16 v[10:13], v[228:231], v[182:185], v[10:13]
	v_mfma_f32_16x16x32_bf16 v[6:9], v[220:223], v[190:193], v[6:9]
	v_mfma_f32_16x16x32_bf16 v[2:5], v[228:231], v[190:193], v[2:5]
	v_mfma_f32_16x16x32_bf16 v[30:33], v[224:227], v[166:169], v[30:33]
	v_mfma_f32_16x16x32_bf16 v[26:29], v[232:235], v[166:169], v[26:29]
	v_mfma_f32_16x16x32_bf16 v[22:25], v[224:227], v[174:177], v[22:25]
	v_mfma_f32_16x16x32_bf16 v[18:21], v[232:235], v[174:177], v[18:21]
	v_mfma_f32_16x16x32_bf16 v[14:17], v[224:227], v[186:189], v[14:17]
	v_mfma_f32_16x16x32_bf16 v[10:13], v[232:235], v[186:189], v[10:13]
	v_mfma_f32_16x16x32_bf16 v[6:9], v[224:227], v[194:197], v[6:9]
	v_mfma_f32_16x16x32_bf16 v[2:5], v[232:235], v[194:197], v[2:5]
	s_barrier
	s_add_i32 s52, 0, 0x18000
	ds_read_b128 v[134:137], v250 offset:32768
	ds_read_b128 v[138:141], v250 offset:33792
	ds_read_b128 v[142:145], v250 offset:34816
	ds_read_b128 v[152:155], v250 offset:35840
	s_add_u32 s46, s46, s22
	s_addc_u32 s47, s47, 0
	s_mov_b32 m0, s51
	ds_read_b128 v[162:165], v160 offset:32768
	ds_read_b128 v[166:169], v160 offset:33792
	ds_read_b128 v[170:173], v160 offset:34816
	ds_read_b128 v[174:177], v160 offset:35840
	ds_read_b128 v[182:185], v160 offset:36864
	ds_read_b128 v[186:189], v160 offset:37888
	ds_read_b128 v[190:193], v160 offset:38912
	ds_read_b128 v[194:197], v160 offset:39936
	global_load_lds_dwordx4 v0, s[46:47]
	s_mov_b32 m0, s54
	s_nop 0
	global_load_lds_dwordx4 v146, s[46:47]
	s_waitcnt lgkmcnt(8)
	s_barrier
	s_waitcnt lgkmcnt(0)
	v_mfma_f32_16x16x32_bf16 v[126:129], v[134:137], v[162:165], v[126:129]
	v_mfma_f32_16x16x32_bf16 v[122:125], v[142:145], v[162:165], v[122:125]
	v_mfma_f32_16x16x32_bf16 v[118:121], v[134:137], v[170:173], v[118:121]
	v_mfma_f32_16x16x32_bf16 v[114:117], v[142:145], v[170:173], v[114:117]
	v_mfma_f32_16x16x32_bf16 v[110:113], v[134:137], v[182:185], v[110:113]
	v_mfma_f32_16x16x32_bf16 v[106:109], v[142:145], v[182:185], v[106:109]
	v_mfma_f32_16x16x32_bf16 v[102:105], v[134:137], v[190:193], v[102:105]
	v_mfma_f32_16x16x32_bf16 v[98:101], v[142:145], v[190:193], v[98:101]
	v_mfma_f32_16x16x32_bf16 v[126:129], v[138:141], v[166:169], v[126:129]
	v_mfma_f32_16x16x32_bf16 v[122:125], v[152:155], v[166:169], v[122:125]
	v_mfma_f32_16x16x32_bf16 v[118:121], v[138:141], v[174:177], v[118:121]
	v_mfma_f32_16x16x32_bf16 v[114:117], v[152:155], v[174:177], v[114:117]
	v_mfma_f32_16x16x32_bf16 v[110:113], v[138:141], v[186:189], v[110:113]
	v_mfma_f32_16x16x32_bf16 v[106:109], v[152:155], v[186:189], v[106:109]
	v_mfma_f32_16x16x32_bf16 v[102:105], v[138:141], v[194:197], v[102:105]
	v_mfma_f32_16x16x32_bf16 v[98:101], v[152:155], v[194:197], v[98:101]
	s_barrier
	s_add_i32 s46, 0, 0x1c000
	s_add_i32 s47, s52, s24
	s_mov_b32 m0, s47
	ds_read_b128 v[220:223], v250 offset:49152
	ds_read_b128 v[224:227], v250 offset:50176
	ds_read_b128 v[228:231], v250 offset:51200
	ds_read_b128 v[232:235], v250 offset:52224
	global_load_lds_dwordx4 v0, s[98:99]
	s_add_i32 m0, s47, 0x2000
	s_nop 0
	global_load_lds_dwordx4 v146, s[98:99]
	s_barrier
; #define PG8_STAGE(bufoff, gbase, voff) do { _Pragma("unroll") for (int _i = 0; _i < 2; ++_i) \
;         __builtin_amdgcn_global_load_lds((const unsigned*)((const char*)(gbase) + (voff)[_i]), (LAS unsigned*)(lds + (bufoff) + ldsw + _i * 8192), 16, 0, 0); } while (0)
; #define PG8_MMA(ai, bj, At, Bt) do { __builtin_amdgcn_s_setprio(1); _Pragma("unroll") for (int m = 0; m < 4; ++m) _Pragma("unroll") for (int n = 0; n < 2; ++n) _Pragma("unroll") for (int k = 0; k < 2; ++k) \
;         acc[ai][bj][m][n] = __builtin_amdgcn_mfma_f32_16x16x32_bf16(Bt[n][k], At[m][k], acc[ai][bj][m][n], 0, 0, 0); __builtin_amdgcn_s_setprio(0); } while (0)
; #define PG8_WAIT_V(n) asm volatile("s_waitcnt vmcnt(" #n ")" ::: "memory")
; #define PG8_WAIT_L(n) asm volatile("s_waitcnt lgkmcnt(" #n ")" ::: "memory")
; #define PG8_BAR __builtin_amdgcn_s_barrier()
; #define PG8_SCHED __builtin_amdgcn_sched_barrier(0)
;     template <int mode> __device__ __forceinline__ void run(const f32x4 (&acc)[2][2][4][2], const Unit& u, int wr, int wc, int fr, int fq, const LAS float* sc) const {
;     ...
;             const int col0 = u.pn * BM + wc * 32 + 8 * fq;
;             f32x4 bv[2][2];
; #pragma unroll
;             for (int bj = 0; bj < 2; ++bj)
; #pragma unroll
;                 for (int n = 0; n < 2; ++n) bv[bj][n] = bias ? *(const f32x4*)(bias + col0 + bj * HALF + 4 * n) : (f32x4){0.f, 0.f, 0.f, 0.f};
; template <int MODE, class EpiT, class Sched>
; __device__ __forceinline__ void gemm_phase(LAS unsigned char* lds, const Gemm g, const Sched& S, const EpiT& E) {
;     ...
;             PG8_BAR; PG8_WAIT_L(0); PG8_MMA(1, 0, At, B0); PG8_BAR; PG8_SCHED;
;             PG8_STAGE(PG8_SB(1, 1), b3 + hstep, voffB);
;             PG8_WAIT_V(6); PG8_BAR; PG8_MMA(1, 1, At, B1); PG8_BAR;
;         }
	s_waitcnt lgkmcnt(0)
	v_mfma_f32_16x16x32_bf16 v[94:97], v[220:223], v[162:165], v[94:97]
	v_mfma_f32_16x16x32_bf16 v[90:93], v[228:231], v[162:165], v[90:93]
	v_mfma_f32_16x16x32_bf16 v[86:89], v[220:223], v[170:173], v[86:89]
	v_mfma_f32_16x16x32_bf16 v[82:85], v[228:231], v[170:173], v[82:85]
	v_mfma_f32_16x16x32_bf16 v[78:81], v[220:223], v[182:185], v[78:81]
	v_mfma_f32_16x16x32_bf16 v[74:77], v[228:231], v[182:185], v[74:77]
	v_mfma_f32_16x16x32_bf16 v[70:73], v[220:223], v[190:193], v[70:73]
	v_mfma_f32_16x16x32_bf16 v[66:69], v[228:231], v[190:193], v[66:69]
	v_mfma_f32_16x16x32_bf16 v[94:97], v[224:227], v[166:169], v[94:97]
	v_mfma_f32_16x16x32_bf16 v[90:93], v[232:235], v[166:169], v[90:93]
	v_mfma_f32_16x16x32_bf16 v[86:89], v[224:227], v[174:177], v[86:89]
	v_mfma_f32_16x16x32_bf16 v[82:85], v[232:235], v[174:177], v[82:85]
	v_mfma_f32_16x16x32_bf16 v[78:81], v[224:227], v[186:189], v[78:81]
	v_mfma_f32_16x16x32_bf16 v[74:77], v[232:235], v[186:189], v[74:77]
	v_mfma_f32_16x16x32_bf16 v[70:73], v[224:227], v[194:197], v[70:73]
	v_mfma_f32_16x16x32_bf16 v[66:69], v[232:235], v[194:197], v[66:69]
	s_barrier
	s_mov_b32 m0, s56
	ds_read_b128 v[162:165], v160 offset:49152
	ds_read_b128 v[166:169], v160 offset:50176
	ds_read_b128 v[170:173], v160 offset:51200
	ds_read_b128 v[174:177], v160 offset:52224
	ds_read_b128 v[182:185], v160 offset:53248
	ds_read_b128 v[186:189], v160 offset:54272
	ds_read_b128 v[190:193], v160 offset:55296
	ds_read_b128 v[194:197], v160 offset:56320
	global_load_lds_dwordx4 v0, s[100:101]
	s_mov_b32 m0, s57
	s_nop 0
	global_load_lds_dwordx4 v146, s[100:101]
	s_barrier
	s_waitcnt lgkmcnt(0)
	v_mfma_f32_16x16x32_bf16 v[62:65], v[134:137], v[162:165], v[62:65]
	v_mfma_f32_16x16x32_bf16 v[58:61], v[142:145], v[162:165], v[58:61]
	v_mfma_f32_16x16x32_bf16 v[54:57], v[134:137], v[170:173], v[54:57]
	v_mfma_f32_16x16x32_bf16 v[50:53], v[142:145], v[170:173], v[50:53]
	v_mfma_f32_16x16x32_bf16 v[46:49], v[134:137], v[182:185], v[46:49]
	v_mfma_f32_16x16x32_bf16 v[42:45], v[142:145], v[182:185], v[42:45]
	v_mfma_f32_16x16x32_bf16 v[38:41], v[134:137], v[190:193], v[38:41]
	v_mfma_f32_16x16x32_bf16 v[34:37], v[142:145], v[190:193], v[34:37]
	v_mfma_f32_16x16x32_bf16 v[62:65], v[138:141], v[166:169], v[62:65]
	v_mfma_f32_16x16x32_bf16 v[58:61], v[152:155], v[166:169], v[58:61]
	v_mfma_f32_16x16x32_bf16 v[54:57], v[138:141], v[174:177], v[54:57]
	v_mfma_f32_16x16x32_bf16 v[50:53], v[152:155], v[174:177], v[50:53]
	v_mfma_f32_16x16x32_bf16 v[46:49], v[138:141], v[186:189], v[46:49]
	v_mfma_f32_16x16x32_bf16 v[42:45], v[152:155], v[186:189], v[42:45]
	v_mfma_f32_16x16x32_bf16 v[38:41], v[138:141], v[194:197], v[38:41]
	v_mfma_f32_16x16x32_bf16 v[34:37], v[152:155], v[194:197], v[34:37]
	s_barrier
	s_add_i32 s46, s46, s24
	s_add_u32 s98, s98, s22
	s_addc_u32 s99, s99, 0
	s_mov_b32 m0, s46
	s_nop 0
	global_load_lds_dwordx4 v0, s[98:99]
	s_add_i32 m0, s46, 0x2000
	s_nop 0
	global_load_lds_dwordx4 v146, s[98:99]
	s_waitcnt vmcnt(6)
	s_barrier
	v_mfma_f32_16x16x32_bf16 v[30:33], v[220:223], v[162:165], v[30:33]
	v_mfma_f32_16x16x32_bf16 v[26:29], v[228:231], v[162:165], v[26:29]
	v_mfma_f32_16x16x32_bf16 v[22:25], v[220:223], v[170:173], v[22:25]
	v_mfma_f32_16x16x32_bf16 v[18:21], v[228:231], v[170:173], v[18:21]
	v_mfma_f32_16x16x32_bf16 v[14:17], v[220:223], v[182:185], v[14:17]
	v_mfma_f32_16x16x32_bf16 v[10:13], v[228:231], v[182:185], v[10:13]
	v_mfma_f32_16x16x32_bf16 v[6:9], v[220:223], v[190:193], v[6:9]
	v_mfma_f32_16x16x32_bf16 v[2:5], v[228:231], v[190:193], v[2:5]
	v_mfma_f32_16x16x32_bf16 v[30:33], v[224:227], v[166:169], v[30:33]
	v_mfma_f32_16x16x32_bf16 v[26:29], v[232:235], v[166:169], v[26:29]
	v_mfma_f32_16x16x32_bf16 v[22:25], v[224:227], v[174:177], v[22:25]
	v_mfma_f32_16x16x32_bf16 v[18:21], v[232:235], v[174:177], v[18:21]
	v_mfma_f32_16x16x32_bf16 v[14:17], v[224:227], v[186:189], v[14:17]
	v_mfma_f32_16x16x32_bf16 v[10:13], v[232:235], v[186:189], v[10:13]
	v_mfma_f32_16x16x32_bf16 v[6:9], v[224:227], v[194:197], v[6:9]
	v_mfma_f32_16x16x32_bf16 v[2:5], v[232:235], v[194:197], v[2:5]
	s_barrier
	s_add_u32 s44, s44, 0x100
	s_addc_u32 s45, s45, 0
	s_cmp_ge_u32 s68, s55
	s_mov_b32 s46, s68
	s_cbranch_scc0 .LBB0_280
	v_lshl_or_b32 v152, s3, 8, v159
	v_ashrrev_i32_e32 v153, 31, v152
	v_cndmask_b32_e64 v131, 0, 1, s[28:29]
	v_lshl_add_u64 v[154:155], v[152:153], 2, s[12:13]
	v_mov_b32_e32 v130, 0
	v_cmp_ne_u32_e64 s[44:45], 1, v131
	s_andn2_b64 vcc, exec, s[28:29]
	v_mov_b32_e32 v134, 0
	v_mov_b32_e32 v135, 0
	v_mov_b32_e32 v136, 0
	v_mov_b32_e32 v137, 0
	s_cbranch_vccnz .LBB0_283
	global_load_dwordx4 v[134:137], v[154:155], off
